# prompt pooling branch of phase 4 rewritten: all row loads issued up front instead of 47 serialized round trips
# speedup vs baseline: 1.0144x; 1.0144x over previous
; template <int NTOK, bool SMP>
; __device__ __forceinline__ void mixer_item(const Params& p, int it) {
;     ...
;         const int pc = (tid - 384) * 8, gi = pc >> 8, w = 2 << gi;
;         const int seqrow0 = SMP ? TP + sb * 4 : b * 2048;
;         const float* sp = p.in[6] + (size_t)sb * 15 * 1024 + pc;
;         auto xpool = [&](int tt, float* f) {
;             if (tt >= 0) unpack8(*(const u32x4*)(proj + (size_t)(seqrow0 + tt) * NPROJ + C_XP + pc), f);
;             else if (SMP) { const float* s = sp + (size_t)(15 + tt) * 1024;
; #pragma unroll
;                 for (int i = 0; i < 8; ++i) f[i] = s[i]; }
;             else {
; #pragma unroll
;                 for (int i = 0; i < 8; ++i) f[i] = 0.f; }
;         };
;         float s[8];
; #pragma unroll
;         for (int i = 0; i < 8; ++i) s[i] = 0.f;
; #pragma unroll
;         for (int q = 1; q < 16; ++q) if (q < w) { float f[8]; xpool(t0 - q, f);
; #pragma unroll
;             for (int i = 0; i < 8; ++i) s[i] += f[i]; }
; #pragma unroll 4
;         for (int t = 0; t < NTOK; ++t) {
;             const int tt = t0 + t; float x[8], y[8], f[8];
;             xpool(tt, x);
;             const float cnt = SMP ? (float)w : (float)min(w, tt + 1); const float ic = 1.0f / cnt;
; #pragma unroll
;             for (int i = 0; i < 8; ++i) { s[i] += x[i]; y[i] = s[i] * ic - x[i]; }
.LBB0_544:
	s_or_b64 exec, exec, s[22:23]
	s_and_saveexec_b64 s[22:23], s[10:11]
	s_xor_b64 s[62:63], exec, s[22:23]
	s_cbranch_execz .LBB0_637
	v_readfirstlane_b32 s74, v160
	s_cmpk_ge_u32 s74, 0x1c0
	s_cbranch_scc1 .Lpl_w7
	s_mul_i32 s64, s60, 0x4a00
	s_mul_hi_u32 s65, s60, 0x4a00
	s_add_u32 s64, s64, s30
	s_addc_u32 s65, s65, s31
	s_add_u32 s64, s64, 0x2000
	s_addc_u32 s65, s65, 0
	s_mov_b32 s72, 0
	s_mov_b32 s73, -1
	s_mov_b64 s[76:77], exec
	s_cmp_eq_u32 s40, 0
	s_cselect_b64 s[78:79], -1, 0
	s_cbranch_scc1 .Lpl_w6_zeroP
	s_mov_b64 s[66:67], s[64:65]
	s_sub_u32 s66, s66, 0x4a00
	s_subb_u32 s67, s67, 0
	global_load_dwordx4 v[56:59], v82, s[66:67]
	s_sub_u32 s66, s66, 0x4a00
	s_subb_u32 s67, s67, 0
	global_load_dwordx4 v[52:55], v82, s[66:67]
	s_sub_u32 s66, s66, 0x4a00
	s_subb_u32 s67, s67, 0
	global_load_dwordx4 v[48:51], v82, s[66:67]
	s_branch .Lpl_w6_loadX
.Lpl_w6_zeroP:
	v_mov_b32_e32 v56, 0
	v_mov_b32_e32 v57, 0
	v_mov_b32_e32 v58, 0
	v_mov_b32_e32 v59, 0
	v_mov_b32_e32 v52, 0
	v_mov_b32_e32 v53, 0
	v_mov_b32_e32 v54, 0
	v_mov_b32_e32 v55, 0
	v_mov_b32_e32 v48, 0
	v_mov_b32_e32 v49, 0
	v_mov_b32_e32 v50, 0
	v_mov_b32_e32 v51, 0
.Lpl_w6_loadX:
	s_mov_b64 s[66:67], s[64:65]
	global_load_dwordx4 v[60:63], v82, s[66:67]
	s_add_u32 s66, s66, 0x4a00
	s_addc_u32 s67, s67, 0
	global_load_dwordx4 v[130:133], v82, s[66:67]
	s_add_u32 s66, s66, 0x4a00
	s_addc_u32 s67, s67, 0
	global_load_dwordx4 v[134:137], v82, s[66:67]
	s_add_u32 s66, s66, 0x4a00
	s_addc_u32 s67, s67, 0
	global_load_dwordx4 v[138:141], v82, s[66:67]
	s_add_u32 s66, s66, 0x4a00
	s_addc_u32 s67, s67, 0
	global_load_dwordx4 v[142:145], v82, s[66:67]
	s_add_u32 s66, s66, 0x4a00
	s_addc_u32 s67, s67, 0
	global_load_dwordx4 v[146:149], v82, s[66:67]
	s_add_u32 s66, s66, 0x4a00
	s_addc_u32 s67, s67, 0
	global_load_dwordx4 v[150:153], v82, s[66:67]
	s_add_u32 s66, s66, 0x4a00
	s_addc_u32 s67, s67, 0
	global_load_dwordx4 v[154:157], v82, s[66:67]
	s_add_u32 s66, s66, 0x4a00
	s_addc_u32 s67, s67, 0
	global_load_dwordx4 v[162:165], v82, s[66:67]
	s_add_u32 s66, s66, 0x4a00
	s_addc_u32 s67, s67, 0
	global_load_dwordx4 v[176:179], v82, s[66:67]
	s_add_u32 s66, s66, 0x4a00
	s_addc_u32 s67, s67, 0
	global_load_dwordx4 v[180:183], v82, s[66:67]
	s_add_u32 s66, s66, 0x4a00
	s_addc_u32 s67, s67, 0
	global_load_dwordx4 v[186:189], v82, s[66:67]
	s_add_u32 s66, s66, 0x4a00
	s_addc_u32 s67, s67, 0
	global_load_dwordx4 v[190:193], v82, s[66:67]
	s_add_u32 s66, s66, 0x4a00
	s_addc_u32 s67, s67, 0
	global_load_dwordx4 v[194:197], v82, s[66:67]
	s_add_u32 s66, s66, 0x4a00
	s_addc_u32 s67, s67, 0
	global_load_dwordx4 v[198:201], v82, s[66:67]
	s_add_u32 s66, s66, 0x4a00
	s_addc_u32 s67, s67, 0
	global_load_dwordx4 v[202:205], v82, s[66:67]
	s_lshl_b32 s68, s60, 11
	s_add_u32 s68, s68, s26
	s_addc_u32 s69, s27, 0
	s_add_u32 s68, s68, 0xd439000
	s_addc_u32 s69, s69, 0
	s_mul_i32 s70, s91, 15
	s_add_i32 s70, s70, -1
	s_ashr_i32 s71, s70, 31
	s_lshl_b64 s[70:71], s[70:71], 12
	s_add_u32 s70, s70, s24
	s_addc_u32 s71, s71, s25
	s_add_u32 s70, s70, 0x4624000
	s_addc_u32 s71, s71, 0
	v_lshlrev_b32_e32 v185, 1, v82
	s_waitcnt vmcnt(18)
	v_lshlrev_b32_e32 v230, 16, v56
	v_and_b32_e32 v231, 0xffff0000, v56
	v_pk_add_f32 v[206:207], v[230:231], 0 op_sel_hi:[1,0]
	v_lshlrev_b32_e32 v230, 16, v57
	v_and_b32_e32 v231, 0xffff0000, v57
	v_pk_add_f32 v[208:209], v[230:231], 0 op_sel_hi:[1,0]
	v_lshlrev_b32_e32 v230, 16, v58
	v_and_b32_e32 v231, 0xffff0000, v58
	v_pk_add_f32 v[210:211], v[230:231], 0 op_sel_hi:[1,0]
	v_lshlrev_b32_e32 v230, 16, v59
	v_and_b32_e32 v231, 0xffff0000, v59
	v_pk_add_f32 v[212:213], v[230:231], 0 op_sel_hi:[1,0]
	s_mov_b64 exec, s[72:73]
	s_waitcnt vmcnt(17)
	v_lshlrev_b32_e32 v230, 16, v52
	v_and_b32_e32 v231, 0xffff0000, v52
	v_pk_add_f32 v[206:207], v[206:207], v[230:231]
	v_lshlrev_b32_e32 v230, 16, v53
	v_and_b32_e32 v231, 0xffff0000, v53
	v_pk_add_f32 v[208:209], v[208:209], v[230:231]
	v_lshlrev_b32_e32 v230, 16, v54
	v_and_b32_e32 v231, 0xffff0000, v54
	v_pk_add_f32 v[210:211], v[210:211], v[230:231]
	v_lshlrev_b32_e32 v230, 16, v55
	v_and_b32_e32 v231, 0xffff0000, v55
	v_pk_add_f32 v[212:213], v[212:213], v[230:231]
	s_waitcnt vmcnt(16)
	v_lshlrev_b32_e32 v230, 16, v48
	v_and_b32_e32 v231, 0xffff0000, v48
	v_pk_add_f32 v[206:207], v[206:207], v[230:231]
	v_lshlrev_b32_e32 v230, 16, v49
	v_and_b32_e32 v231, 0xffff0000, v49
	v_pk_add_f32 v[208:209], v[208:209], v[230:231]
	v_lshlrev_b32_e32 v230, 16, v50
	v_and_b32_e32 v231, 0xffff0000, v50
	v_pk_add_f32 v[210:211], v[210:211], v[230:231]
	v_lshlrev_b32_e32 v230, 16, v51
	v_and_b32_e32 v231, 0xffff0000, v51
	v_pk_add_f32 v[212:213], v[212:213], v[230:231]
	s_mov_b64 exec, s[76:77]
	s_waitcnt vmcnt(15)
; __device__ __forceinline__ u32x4 pack8(const float* f) { u32x4 w; w.x = pk2(f[0], f[1]); w.y = pk2(f[2], f[3]); w.z = pk2(f[4], f[5]); w.w = pk2(f[6], f[7]); return w; }
; template <int NTOK, bool SMP>
; __device__ __forceinline__ void mixer_item(const Params& p, int it) {
;     ...
;         for (int t = 0; t < NTOK; ++t) {
;             const int tt = t0 + t; float x[8], y[8], f[8];
;             xpool(tt, x);
;             const float cnt = SMP ? (float)w : (float)min(w, tt + 1); const float ic = 1.0f / cnt;
; #pragma unroll
;             for (int i = 0; i < 8; ++i) { s[i] += x[i]; y[i] = s[i] * ic - x[i]; }
;             *(u32x4*)(yp + (size_t)(seqrow0 + tt) * 1024 + pc) = pack8(y);
;             xpool(tt - w + 1, f);
; #pragma unroll
;             for (int i = 0; i < 8; ++i) s[i] -= f[i];
;             if (SMP) { float* o = p.out + O_PS + ((size_t)sb * 15 + 11 + t) * 1024 + pc; *(f32x4*)o = (f32x4){x[0], x[1], x[2], x[3]}; *(f32x4*)(o + 4) = (f32x4){x[4], x[5], x[6], x[7]}; }
;             else if (tt >= 2033) { float* o = p.out + O_PP + ((size_t)b * 15 + (tt - 2033)) * 1024 + pc; *(f32x4*)o = (f32x4){x[0], x[1], x[2], x[3]}; *(f32x4*)(o + 4) = (f32x4){x[4], x[5], x[6], x[7]}; }
	v_mov_b32_e32 v175, 0x3f800000
	v_cmp_lt_u32_e32 vcc, 1, v65
	s_and_b64 vcc, vcc, s[78:79]
	s_nop 1
	v_cndmask_b32_e32 v234, v72, v175, vcc
	v_lshlrev_b32_e32 v230, 16, v60
	v_and_b32_e32 v231, 0xffff0000, v60
	v_pk_add_f32 v[206:207], v[206:207], v[230:231]
	v_pk_fma_f32 v[232:233], v[234:235], v[206:207], v[230:231] op_sel_hi:[0,1,1] neg_lo:[0,0,1] neg_hi:[0,0,1]
	v_cvt_pk_bf16_f32 v214, v232, v233
	v_lshlrev_b32_e32 v230, 16, v61
	v_and_b32_e32 v231, 0xffff0000, v61
	v_pk_add_f32 v[208:209], v[208:209], v[230:231]
	v_pk_fma_f32 v[232:233], v[234:235], v[208:209], v[230:231] op_sel_hi:[0,1,1] neg_lo:[0,0,1] neg_hi:[0,0,1]
	v_cvt_pk_bf16_f32 v215, v232, v233
	v_lshlrev_b32_e32 v230, 16, v62
	v_and_b32_e32 v231, 0xffff0000, v62
	v_pk_add_f32 v[210:211], v[210:211], v[230:231]
	v_pk_fma_f32 v[232:233], v[234:235], v[210:211], v[230:231] op_sel_hi:[0,1,1] neg_lo:[0,0,1] neg_hi:[0,0,1]
	v_cvt_pk_bf16_f32 v216, v232, v233
	v_lshlrev_b32_e32 v230, 16, v63
	v_and_b32_e32 v231, 0xffff0000, v63
	v_pk_add_f32 v[212:213], v[212:213], v[230:231]
	v_pk_fma_f32 v[232:233], v[234:235], v[212:213], v[230:231] op_sel_hi:[0,1,1] neg_lo:[0,0,1] neg_hi:[0,0,1]
	v_cvt_pk_bf16_f32 v217, v232, v233
	global_store_dwordx4 v82, v[214:217], s[68:69]
	v_cndmask_b32_e64 v129, v56, v48, s[72:73]
	v_lshlrev_b32_e32 v158, 16, v129
	v_and_b32_e32 v159, 0xffff0000, v129
	v_pk_add_f32 v[206:207], v[206:207], v[158:159] neg_lo:[0,1] neg_hi:[0,1]
	v_cndmask_b32_e64 v129, v57, v49, s[72:73]
	v_lshlrev_b32_e32 v158, 16, v129
	v_and_b32_e32 v159, 0xffff0000, v129
	v_pk_add_f32 v[208:209], v[208:209], v[158:159] neg_lo:[0,1] neg_hi:[0,1]
	v_cndmask_b32_e64 v129, v58, v50, s[72:73]
	v_lshlrev_b32_e32 v158, 16, v129
	v_and_b32_e32 v159, 0xffff0000, v129
	v_pk_add_f32 v[210:211], v[210:211], v[158:159] neg_lo:[0,1] neg_hi:[0,1]
	v_cndmask_b32_e64 v129, v59, v51, s[72:73]
	v_lshlrev_b32_e32 v158, 16, v129
	v_and_b32_e32 v159, 0xffff0000, v129
	v_pk_add_f32 v[212:213], v[212:213], v[158:159] neg_lo:[0,1] neg_hi:[0,1]
	s_waitcnt vmcnt(15)
	v_mov_b32_e32 v175, 0x3f000000
	v_cmp_lt_u32_e32 vcc, 2, v65
	s_and_b64 vcc, vcc, s[78:79]
	s_nop 1
	v_cndmask_b32_e32 v234, v72, v175, vcc
	v_lshlrev_b32_e32 v230, 16, v130
	v_and_b32_e32 v231, 0xffff0000, v130
	v_pk_add_f32 v[206:207], v[206:207], v[230:231]
	v_pk_fma_f32 v[232:233], v[234:235], v[206:207], v[230:231] op_sel_hi:[0,1,1] neg_lo:[0,0,1] neg_hi:[0,0,1]
	v_cvt_pk_bf16_f32 v218, v232, v233
	v_lshlrev_b32_e32 v230, 16, v131
	v_and_b32_e32 v231, 0xffff0000, v131
	v_pk_add_f32 v[208:209], v[208:209], v[230:231]
	v_pk_fma_f32 v[232:233], v[234:235], v[208:209], v[230:231] op_sel_hi:[0,1,1] neg_lo:[0,0,1] neg_hi:[0,0,1]
	v_cvt_pk_bf16_f32 v219, v232, v233
	v_lshlrev_b32_e32 v230, 16, v132
	v_and_b32_e32 v231, 0xffff0000, v132
	v_pk_add_f32 v[210:211], v[210:211], v[230:231]
	v_pk_fma_f32 v[232:233], v[234:235], v[210:211], v[230:231] op_sel_hi:[0,1,1] neg_lo:[0,0,1] neg_hi:[0,0,1]
	v_cvt_pk_bf16_f32 v220, v232, v233
	v_lshlrev_b32_e32 v230, 16, v133
	v_and_b32_e32 v231, 0xffff0000, v133
	v_pk_add_f32 v[212:213], v[212:213], v[230:231]
	v_pk_fma_f32 v[232:233], v[234:235], v[212:213], v[230:231] op_sel_hi:[0,1,1] neg_lo:[0,0,1] neg_hi:[0,0,1]
	v_cvt_pk_bf16_f32 v221, v232, v233
	s_add_u32 s68, s68, 0x800
	s_addc_u32 s69, s69, 0
	global_store_dwordx4 v82, v[218:221], s[68:69]
	s_cmpk_lg_u32 s40, 0x7f0
	s_cbranch_scc1 .Lpl_w6_nopp1
	v_lshlrev_b32_e32 v222, 16, v130
	v_and_b32_e32 v223, 0xffff0000, v130
	v_lshlrev_b32_e32 v224, 16, v131
	v_and_b32_e32 v225, 0xffff0000, v131
	v_lshlrev_b32_e32 v226, 16, v132
	v_and_b32_e32 v227, 0xffff0000, v132
	v_lshlrev_b32_e32 v228, 16, v133
	v_and_b32_e32 v229, 0xffff0000, v133
	s_add_u32 s70, s70, 0x1000
	s_addc_u32 s71, s71, 0
	global_store_dwordx4 v185, v[222:225], s[70:71]
	global_store_dwordx4 v185, v[226:229], s[70:71] offset:16
.Lpl_w6_nopp1:
	v_cndmask_b32_e64 v129, v60, v52, s[72:73]
	v_lshlrev_b32_e32 v158, 16, v129
	v_and_b32_e32 v159, 0xffff0000, v129
	v_pk_add_f32 v[206:207], v[206:207], v[158:159] neg_lo:[0,1] neg_hi:[0,1]
	v_cndmask_b32_e64 v129, v61, v53, s[72:73]
	v_lshlrev_b32_e32 v158, 16, v129
	v_and_b32_e32 v159, 0xffff0000, v129
	v_pk_add_f32 v[208:209], v[208:209], v[158:159] neg_lo:[0,1] neg_hi:[0,1]
	v_cndmask_b32_e64 v129, v62, v54, s[72:73]
	v_lshlrev_b32_e32 v158, 16, v129
	v_and_b32_e32 v159, 0xffff0000, v129
	v_pk_add_f32 v[210:211], v[210:211], v[158:159] neg_lo:[0,1] neg_hi:[0,1]
	v_cndmask_b32_e64 v129, v63, v55, s[72:73]
	v_lshlrev_b32_e32 v158, 16, v129
	v_and_b32_e32 v159, 0xffff0000, v129
	v_pk_add_f32 v[212:213], v[212:213], v[158:159] neg_lo:[0,1] neg_hi:[0,1]
	s_waitcnt vmcnt(15)
	v_mov_b32_e32 v175, 0x3eaaaaab
	v_cmp_lt_u32_e32 vcc, 3, v65
	s_and_b64 vcc, vcc, s[78:79]
	s_nop 1
	v_cndmask_b32_e32 v234, v72, v175, vcc
	v_lshlrev_b32_e32 v230, 16, v134
	v_and_b32_e32 v231, 0xffff0000, v134
	v_pk_add_f32 v[206:207], v[206:207], v[230:231]
	v_pk_fma_f32 v[232:233], v[234:235], v[206:207], v[230:231] op_sel_hi:[0,1,1] neg_lo:[0,0,1] neg_hi:[0,0,1]
	v_cvt_pk_bf16_f32 v214, v232, v233
	v_lshlrev_b32_e32 v230, 16, v135
	v_and_b32_e32 v231, 0xffff0000, v135
	v_pk_add_f32 v[208:209], v[208:209], v[230:231]
	v_pk_fma_f32 v[232:233], v[234:235], v[208:209], v[230:231] op_sel_hi:[0,1,1] neg_lo:[0,0,1] neg_hi:[0,0,1]
	v_cvt_pk_bf16_f32 v215, v232, v233
	v_lshlrev_b32_e32 v230, 16, v136
	v_and_b32_e32 v231, 0xffff0000, v136
	v_pk_add_f32 v[210:211], v[210:211], v[230:231]
	v_pk_fma_f32 v[232:233], v[234:235], v[210:211], v[230:231] op_sel_hi:[0,1,1] neg_lo:[0,0,1] neg_hi:[0,0,1]
	v_cvt_pk_bf16_f32 v216, v232, v233
	v_lshlrev_b32_e32 v230, 16, v137
	v_and_b32_e32 v231, 0xffff0000, v137
	v_pk_add_f32 v[212:213], v[212:213], v[230:231]
	v_pk_fma_f32 v[232:233], v[234:235], v[212:213], v[230:231] op_sel_hi:[0,1,1] neg_lo:[0,0,1] neg_hi:[0,0,1]
	v_cvt_pk_bf16_f32 v217, v232, v233
	s_add_u32 s68, s68, 0x800
	s_addc_u32 s69, s69, 0
	global_store_dwordx4 v82, v[214:217], s[68:69]
	s_cmpk_lg_u32 s40, 0x7f0
	s_cbranch_scc1 .Lpl_w6_nopp2
	v_lshlrev_b32_e32 v222, 16, v134
	v_and_b32_e32 v223, 0xffff0000, v134
	v_lshlrev_b32_e32 v224, 16, v135
	v_and_b32_e32 v225, 0xffff0000, v135
	v_lshlrev_b32_e32 v226, 16, v136
	v_and_b32_e32 v227, 0xffff0000, v136
	v_lshlrev_b32_e32 v228, 16, v137
	v_and_b32_e32 v229, 0xffff0000, v137
	s_add_u32 s70, s70, 0x1000
	s_addc_u32 s71, s71, 0
	global_store_dwordx4 v185, v[222:225], s[70:71]
	global_store_dwordx4 v185, v[226:229], s[70:71] offset:16
; __device__ __forceinline__ u32x4 pack8(const float* f) { u32x4 w; w.x = pk2(f[0], f[1]); w.y = pk2(f[2], f[3]); w.z = pk2(f[4], f[5]); w.w = pk2(f[6], f[7]); return w; }
; template <int NTOK, bool SMP>
; __device__ __forceinline__ void mixer_item(const Params& p, int it) {
;     ...
;         for (int t = 0; t < NTOK; ++t) {
;             const int tt = t0 + t; float x[8], y[8], f[8];
;             xpool(tt, x);
;             const float cnt = SMP ? (float)w : (float)min(w, tt + 1); const float ic = 1.0f / cnt;
; #pragma unroll
;             for (int i = 0; i < 8; ++i) { s[i] += x[i]; y[i] = s[i] * ic - x[i]; }
;             *(u32x4*)(yp + (size_t)(seqrow0 + tt) * 1024 + pc) = pack8(y);
;             xpool(tt - w + 1, f);
; #pragma unroll
;             for (int i = 0; i < 8; ++i) s[i] -= f[i];
;             if (SMP) { float* o = p.out + O_PS + ((size_t)sb * 15 + 11 + t) * 1024 + pc; *(f32x4*)o = (f32x4){x[0], x[1], x[2], x[3]}; *(f32x4*)(o + 4) = (f32x4){x[4], x[5], x[6], x[7]}; }
;             else if (tt >= 2033) { float* o = p.out + O_PP + ((size_t)b * 15 + (tt - 2033)) * 1024 + pc; *(f32x4*)o = (f32x4){x[0], x[1], x[2], x[3]}; *(f32x4*)(o + 4) = (f32x4){x[4], x[5], x[6], x[7]}; }
.Lpl_w6_nopp2:
	v_cndmask_b32_e64 v129, v130, v56, s[72:73]
	v_lshlrev_b32_e32 v158, 16, v129
	v_and_b32_e32 v159, 0xffff0000, v129
	v_pk_add_f32 v[206:207], v[206:207], v[158:159] neg_lo:[0,1] neg_hi:[0,1]
	v_cndmask_b32_e64 v129, v131, v57, s[72:73]
	v_lshlrev_b32_e32 v158, 16, v129
	v_and_b32_e32 v159, 0xffff0000, v129
	v_pk_add_f32 v[208:209], v[208:209], v[158:159] neg_lo:[0,1] neg_hi:[0,1]
	v_cndmask_b32_e64 v129, v132, v58, s[72:73]
	v_lshlrev_b32_e32 v158, 16, v129
	v_and_b32_e32 v159, 0xffff0000, v129
	v_pk_add_f32 v[210:211], v[210:211], v[158:159] neg_lo:[0,1] neg_hi:[0,1]
	v_cndmask_b32_e64 v129, v133, v59, s[72:73]
	v_lshlrev_b32_e32 v158, 16, v129
	v_and_b32_e32 v159, 0xffff0000, v129
	v_pk_add_f32 v[212:213], v[212:213], v[158:159] neg_lo:[0,1] neg_hi:[0,1]
	s_waitcnt vmcnt(15)
	v_lshlrev_b32_e32 v230, 16, v138
	v_and_b32_e32 v231, 0xffff0000, v138
	v_pk_add_f32 v[206:207], v[206:207], v[230:231]
	v_pk_fma_f32 v[232:233], v[72:73], v[206:207], v[230:231] op_sel_hi:[0,1,1] neg_lo:[0,0,1] neg_hi:[0,0,1]
	v_cvt_pk_bf16_f32 v218, v232, v233
	v_lshlrev_b32_e32 v230, 16, v139
	v_and_b32_e32 v231, 0xffff0000, v139
	v_pk_add_f32 v[208:209], v[208:209], v[230:231]
	v_pk_fma_f32 v[232:233], v[72:73], v[208:209], v[230:231] op_sel_hi:[0,1,1] neg_lo:[0,0,1] neg_hi:[0,0,1]
	v_cvt_pk_bf16_f32 v219, v232, v233
	v_lshlrev_b32_e32 v230, 16, v140
	v_and_b32_e32 v231, 0xffff0000, v140
	v_pk_add_f32 v[210:211], v[210:211], v[230:231]
	v_pk_fma_f32 v[232:233], v[72:73], v[210:211], v[230:231] op_sel_hi:[0,1,1] neg_lo:[0,0,1] neg_hi:[0,0,1]
	v_cvt_pk_bf16_f32 v220, v232, v233
	v_lshlrev_b32_e32 v230, 16, v141
	v_and_b32_e32 v231, 0xffff0000, v141
	v_pk_add_f32 v[212:213], v[212:213], v[230:231]
	v_pk_fma_f32 v[232:233], v[72:73], v[212:213], v[230:231] op_sel_hi:[0,1,1] neg_lo:[0,0,1] neg_hi:[0,0,1]
	v_cvt_pk_bf16_f32 v221, v232, v233
	s_add_u32 s68, s68, 0x800
	s_addc_u32 s69, s69, 0
	global_store_dwordx4 v82, v[218:221], s[68:69]
	s_cmpk_lg_u32 s40, 0x7f0
	s_cbranch_scc1 .Lpl_w6_nopp3
	v_lshlrev_b32_e32 v222, 16, v138
	v_and_b32_e32 v223, 0xffff0000, v138
	v_lshlrev_b32_e32 v224, 16, v139
	v_and_b32_e32 v225, 0xffff0000, v139
	v_lshlrev_b32_e32 v226, 16, v140
	v_and_b32_e32 v227, 0xffff0000, v140
	v_lshlrev_b32_e32 v228, 16, v141
	v_and_b32_e32 v229, 0xffff0000, v141
	s_add_u32 s70, s70, 0x1000
	s_addc_u32 s71, s71, 0
	global_store_dwordx4 v185, v[222:225], s[70:71]
	global_store_dwordx4 v185, v[226:229], s[70:71] offset:16
.Lpl_w6_nopp3:
	v_cndmask_b32_e64 v129, v134, v60, s[72:73]
	v_lshlrev_b32_e32 v158, 16, v129
	v_and_b32_e32 v159, 0xffff0000, v129
	v_pk_add_f32 v[206:207], v[206:207], v[158:159] neg_lo:[0,1] neg_hi:[0,1]
	v_cndmask_b32_e64 v129, v135, v61, s[72:73]
	v_lshlrev_b32_e32 v158, 16, v129
	v_and_b32_e32 v159, 0xffff0000, v129
	v_pk_add_f32 v[208:209], v[208:209], v[158:159] neg_lo:[0,1] neg_hi:[0,1]
	v_cndmask_b32_e64 v129, v136, v62, s[72:73]
	v_lshlrev_b32_e32 v158, 16, v129
	v_and_b32_e32 v159, 0xffff0000, v129
	v_pk_add_f32 v[210:211], v[210:211], v[158:159] neg_lo:[0,1] neg_hi:[0,1]
	v_cndmask_b32_e64 v129, v137, v63, s[72:73]
	v_lshlrev_b32_e32 v158, 16, v129
	v_and_b32_e32 v159, 0xffff0000, v129
	v_pk_add_f32 v[212:213], v[212:213], v[158:159] neg_lo:[0,1] neg_hi:[0,1]
	s_waitcnt vmcnt(15)
	v_lshlrev_b32_e32 v230, 16, v142
	v_and_b32_e32 v231, 0xffff0000, v142
	v_pk_add_f32 v[206:207], v[206:207], v[230:231]
	v_pk_fma_f32 v[232:233], v[72:73], v[206:207], v[230:231] op_sel_hi:[0,1,1] neg_lo:[0,0,1] neg_hi:[0,0,1]
	v_cvt_pk_bf16_f32 v214, v232, v233
	v_lshlrev_b32_e32 v230, 16, v143
	v_and_b32_e32 v231, 0xffff0000, v143
	v_pk_add_f32 v[208:209], v[208:209], v[230:231]
	v_pk_fma_f32 v[232:233], v[72:73], v[208:209], v[230:231] op_sel_hi:[0,1,1] neg_lo:[0,0,1] neg_hi:[0,0,1]
	v_cvt_pk_bf16_f32 v215, v232, v233
	v_lshlrev_b32_e32 v230, 16, v144
	v_and_b32_e32 v231, 0xffff0000, v144
	v_pk_add_f32 v[210:211], v[210:211], v[230:231]
	v_pk_fma_f32 v[232:233], v[72:73], v[210:211], v[230:231] op_sel_hi:[0,1,1] neg_lo:[0,0,1] neg_hi:[0,0,1]
	v_cvt_pk_bf16_f32 v216, v232, v233
	v_lshlrev_b32_e32 v230, 16, v145
	v_and_b32_e32 v231, 0xffff0000, v145
	v_pk_add_f32 v[212:213], v[212:213], v[230:231]
	v_pk_fma_f32 v[232:233], v[72:73], v[212:213], v[230:231] op_sel_hi:[0,1,1] neg_lo:[0,0,1] neg_hi:[0,0,1]
	v_cvt_pk_bf16_f32 v217, v232, v233
	s_add_u32 s68, s68, 0x800
	s_addc_u32 s69, s69, 0
	global_store_dwordx4 v82, v[214:217], s[68:69]
	s_cmpk_lg_u32 s40, 0x7f0
	s_cbranch_scc1 .Lpl_w6_nopp4
	v_lshlrev_b32_e32 v222, 16, v142
	v_and_b32_e32 v223, 0xffff0000, v142
	v_lshlrev_b32_e32 v224, 16, v143
	v_and_b32_e32 v225, 0xffff0000, v143
	v_lshlrev_b32_e32 v226, 16, v144
	v_and_b32_e32 v227, 0xffff0000, v144
	v_lshlrev_b32_e32 v228, 16, v145
	v_and_b32_e32 v229, 0xffff0000, v145
	s_add_u32 s70, s70, 0x1000
	s_addc_u32 s71, s71, 0
	global_store_dwordx4 v185, v[222:225], s[70:71]
	global_store_dwordx4 v185, v[226:229], s[70:71] offset:16
; __device__ __forceinline__ u32x4 pack8(const float* f) { u32x4 w; w.x = pk2(f[0], f[1]); w.y = pk2(f[2], f[3]); w.z = pk2(f[4], f[5]); w.w = pk2(f[6], f[7]); return w; }
; template <int NTOK, bool SMP>
; __device__ __forceinline__ void mixer_item(const Params& p, int it) {
;     ...
;         for (int t = 0; t < NTOK; ++t) {
;             const int tt = t0 + t; float x[8], y[8], f[8];
;             xpool(tt, x);
;             const float cnt = SMP ? (float)w : (float)min(w, tt + 1); const float ic = 1.0f / cnt;
; #pragma unroll
;             for (int i = 0; i < 8; ++i) { s[i] += x[i]; y[i] = s[i] * ic - x[i]; }
;             *(u32x4*)(yp + (size_t)(seqrow0 + tt) * 1024 + pc) = pack8(y);
;             xpool(tt - w + 1, f);
; #pragma unroll
;             for (int i = 0; i < 8; ++i) s[i] -= f[i];
;             if (SMP) { float* o = p.out + O_PS + ((size_t)sb * 15 + 11 + t) * 1024 + pc; *(f32x4*)o = (f32x4){x[0], x[1], x[2], x[3]}; *(f32x4*)(o + 4) = (f32x4){x[4], x[5], x[6], x[7]}; }
;             else if (tt >= 2033) { float* o = p.out + O_PP + ((size_t)b * 15 + (tt - 2033)) * 1024 + pc; *(f32x4*)o = (f32x4){x[0], x[1], x[2], x[3]}; *(f32x4*)(o + 4) = (f32x4){x[4], x[5], x[6], x[7]}; }
.Lpl_w6_nopp4:
	v_cndmask_b32_e64 v129, v138, v130, s[72:73]
	v_lshlrev_b32_e32 v158, 16, v129
	v_and_b32_e32 v159, 0xffff0000, v129
	v_pk_add_f32 v[206:207], v[206:207], v[158:159] neg_lo:[0,1] neg_hi:[0,1]
	v_cndmask_b32_e64 v129, v139, v131, s[72:73]
	v_lshlrev_b32_e32 v158, 16, v129
	v_and_b32_e32 v159, 0xffff0000, v129
	v_pk_add_f32 v[208:209], v[208:209], v[158:159] neg_lo:[0,1] neg_hi:[0,1]
	v_cndmask_b32_e64 v129, v140, v132, s[72:73]
	v_lshlrev_b32_e32 v158, 16, v129
	v_and_b32_e32 v159, 0xffff0000, v129
	v_pk_add_f32 v[210:211], v[210:211], v[158:159] neg_lo:[0,1] neg_hi:[0,1]
	v_cndmask_b32_e64 v129, v141, v133, s[72:73]
	v_lshlrev_b32_e32 v158, 16, v129
	v_and_b32_e32 v159, 0xffff0000, v129
	v_pk_add_f32 v[212:213], v[212:213], v[158:159] neg_lo:[0,1] neg_hi:[0,1]
	s_waitcnt vmcnt(15)
	v_lshlrev_b32_e32 v230, 16, v146
	v_and_b32_e32 v231, 0xffff0000, v146
	v_pk_add_f32 v[206:207], v[206:207], v[230:231]
	v_pk_fma_f32 v[232:233], v[72:73], v[206:207], v[230:231] op_sel_hi:[0,1,1] neg_lo:[0,0,1] neg_hi:[0,0,1]
	v_cvt_pk_bf16_f32 v218, v232, v233
	v_lshlrev_b32_e32 v230, 16, v147
	v_and_b32_e32 v231, 0xffff0000, v147
	v_pk_add_f32 v[208:209], v[208:209], v[230:231]
	v_pk_fma_f32 v[232:233], v[72:73], v[208:209], v[230:231] op_sel_hi:[0,1,1] neg_lo:[0,0,1] neg_hi:[0,0,1]
	v_cvt_pk_bf16_f32 v219, v232, v233
	v_lshlrev_b32_e32 v230, 16, v148
	v_and_b32_e32 v231, 0xffff0000, v148
	v_pk_add_f32 v[210:211], v[210:211], v[230:231]
	v_pk_fma_f32 v[232:233], v[72:73], v[210:211], v[230:231] op_sel_hi:[0,1,1] neg_lo:[0,0,1] neg_hi:[0,0,1]
	v_cvt_pk_bf16_f32 v220, v232, v233
	v_lshlrev_b32_e32 v230, 16, v149
	v_and_b32_e32 v231, 0xffff0000, v149
	v_pk_add_f32 v[212:213], v[212:213], v[230:231]
	v_pk_fma_f32 v[232:233], v[72:73], v[212:213], v[230:231] op_sel_hi:[0,1,1] neg_lo:[0,0,1] neg_hi:[0,0,1]
	v_cvt_pk_bf16_f32 v221, v232, v233
	s_add_u32 s68, s68, 0x800
	s_addc_u32 s69, s69, 0
	global_store_dwordx4 v82, v[218:221], s[68:69]
	s_cmpk_lg_u32 s40, 0x7f0
	s_cbranch_scc1 .Lpl_w6_nopp5
	v_lshlrev_b32_e32 v222, 16, v146
	v_and_b32_e32 v223, 0xffff0000, v146
	v_lshlrev_b32_e32 v224, 16, v147
	v_and_b32_e32 v225, 0xffff0000, v147
	v_lshlrev_b32_e32 v226, 16, v148
	v_and_b32_e32 v227, 0xffff0000, v148
	v_lshlrev_b32_e32 v228, 16, v149
	v_and_b32_e32 v229, 0xffff0000, v149
	s_add_u32 s70, s70, 0x1000
	s_addc_u32 s71, s71, 0
	global_store_dwordx4 v185, v[222:225], s[70:71]
	global_store_dwordx4 v185, v[226:229], s[70:71] offset:16
.Lpl_w6_nopp5:
	v_cndmask_b32_e64 v129, v142, v134, s[72:73]
	v_lshlrev_b32_e32 v158, 16, v129
	v_and_b32_e32 v159, 0xffff0000, v129
	v_pk_add_f32 v[206:207], v[206:207], v[158:159] neg_lo:[0,1] neg_hi:[0,1]
	v_cndmask_b32_e64 v129, v143, v135, s[72:73]
	v_lshlrev_b32_e32 v158, 16, v129
	v_and_b32_e32 v159, 0xffff0000, v129
	v_pk_add_f32 v[208:209], v[208:209], v[158:159] neg_lo:[0,1] neg_hi:[0,1]
	v_cndmask_b32_e64 v129, v144, v136, s[72:73]
	v_lshlrev_b32_e32 v158, 16, v129
	v_and_b32_e32 v159, 0xffff0000, v129
	v_pk_add_f32 v[210:211], v[210:211], v[158:159] neg_lo:[0,1] neg_hi:[0,1]
	v_cndmask_b32_e64 v129, v145, v137, s[72:73]
	v_lshlrev_b32_e32 v158, 16, v129
	v_and_b32_e32 v159, 0xffff0000, v129
	v_pk_add_f32 v[212:213], v[212:213], v[158:159] neg_lo:[0,1] neg_hi:[0,1]
	s_waitcnt vmcnt(15)
	v_lshlrev_b32_e32 v230, 16, v150
	v_and_b32_e32 v231, 0xffff0000, v150
	v_pk_add_f32 v[206:207], v[206:207], v[230:231]
	v_pk_fma_f32 v[232:233], v[72:73], v[206:207], v[230:231] op_sel_hi:[0,1,1] neg_lo:[0,0,1] neg_hi:[0,0,1]
	v_cvt_pk_bf16_f32 v214, v232, v233
	v_lshlrev_b32_e32 v230, 16, v151
	v_and_b32_e32 v231, 0xffff0000, v151
	v_pk_add_f32 v[208:209], v[208:209], v[230:231]
	v_pk_fma_f32 v[232:233], v[72:73], v[208:209], v[230:231] op_sel_hi:[0,1,1] neg_lo:[0,0,1] neg_hi:[0,0,1]
	v_cvt_pk_bf16_f32 v215, v232, v233
	v_lshlrev_b32_e32 v230, 16, v152
	v_and_b32_e32 v231, 0xffff0000, v152
	v_pk_add_f32 v[210:211], v[210:211], v[230:231]
	v_pk_fma_f32 v[232:233], v[72:73], v[210:211], v[230:231] op_sel_hi:[0,1,1] neg_lo:[0,0,1] neg_hi:[0,0,1]
	v_cvt_pk_bf16_f32 v216, v232, v233
	v_lshlrev_b32_e32 v230, 16, v153
	v_and_b32_e32 v231, 0xffff0000, v153
	v_pk_add_f32 v[212:213], v[212:213], v[230:231]
	v_pk_fma_f32 v[232:233], v[72:73], v[212:213], v[230:231] op_sel_hi:[0,1,1] neg_lo:[0,0,1] neg_hi:[0,0,1]
	v_cvt_pk_bf16_f32 v217, v232, v233
	s_add_u32 s68, s68, 0x800
	s_addc_u32 s69, s69, 0
	global_store_dwordx4 v82, v[214:217], s[68:69]
	s_cmpk_lg_u32 s40, 0x7f0
	s_cbranch_scc1 .Lpl_w6_nopp6
	v_lshlrev_b32_e32 v222, 16, v150
	v_and_b32_e32 v223, 0xffff0000, v150
	v_lshlrev_b32_e32 v224, 16, v151
	v_and_b32_e32 v225, 0xffff0000, v151
	v_lshlrev_b32_e32 v226, 16, v152
	v_and_b32_e32 v227, 0xffff0000, v152
	v_lshlrev_b32_e32 v228, 16, v153
	v_and_b32_e32 v229, 0xffff0000, v153
	s_add_u32 s70, s70, 0x1000
	s_addc_u32 s71, s71, 0
	global_store_dwordx4 v185, v[222:225], s[70:71]
	global_store_dwordx4 v185, v[226:229], s[70:71] offset:16
; __device__ __forceinline__ u32x4 pack8(const float* f) { u32x4 w; w.x = pk2(f[0], f[1]); w.y = pk2(f[2], f[3]); w.z = pk2(f[4], f[5]); w.w = pk2(f[6], f[7]); return w; }
; template <int NTOK, bool SMP>
; __device__ __forceinline__ void mixer_item(const Params& p, int it) {
;     ...
;         for (int t = 0; t < NTOK; ++t) {
;             const int tt = t0 + t; float x[8], y[8], f[8];
;             xpool(tt, x);
;             const float cnt = SMP ? (float)w : (float)min(w, tt + 1); const float ic = 1.0f / cnt;
; #pragma unroll
;             for (int i = 0; i < 8; ++i) { s[i] += x[i]; y[i] = s[i] * ic - x[i]; }
;             *(u32x4*)(yp + (size_t)(seqrow0 + tt) * 1024 + pc) = pack8(y);
;             xpool(tt - w + 1, f);
; #pragma unroll
;             for (int i = 0; i < 8; ++i) s[i] -= f[i];
;             if (SMP) { float* o = p.out + O_PS + ((size_t)sb * 15 + 11 + t) * 1024 + pc; *(f32x4*)o = (f32x4){x[0], x[1], x[2], x[3]}; *(f32x4*)(o + 4) = (f32x4){x[4], x[5], x[6], x[7]}; }
;             else if (tt >= 2033) { float* o = p.out + O_PP + ((size_t)b * 15 + (tt - 2033)) * 1024 + pc; *(f32x4*)o = (f32x4){x[0], x[1], x[2], x[3]}; *(f32x4*)(o + 4) = (f32x4){x[4], x[5], x[6], x[7]}; }
.Lpl_w6_nopp6:
	v_cndmask_b32_e64 v129, v146, v138, s[72:73]
	v_lshlrev_b32_e32 v158, 16, v129
	v_and_b32_e32 v159, 0xffff0000, v129
	v_pk_add_f32 v[206:207], v[206:207], v[158:159] neg_lo:[0,1] neg_hi:[0,1]
	v_cndmask_b32_e64 v129, v147, v139, s[72:73]
	v_lshlrev_b32_e32 v158, 16, v129
	v_and_b32_e32 v159, 0xffff0000, v129
	v_pk_add_f32 v[208:209], v[208:209], v[158:159] neg_lo:[0,1] neg_hi:[0,1]
	v_cndmask_b32_e64 v129, v148, v140, s[72:73]
	v_lshlrev_b32_e32 v158, 16, v129
	v_and_b32_e32 v159, 0xffff0000, v129
	v_pk_add_f32 v[210:211], v[210:211], v[158:159] neg_lo:[0,1] neg_hi:[0,1]
	v_cndmask_b32_e64 v129, v149, v141, s[72:73]
	v_lshlrev_b32_e32 v158, 16, v129
	v_and_b32_e32 v159, 0xffff0000, v129
	v_pk_add_f32 v[212:213], v[212:213], v[158:159] neg_lo:[0,1] neg_hi:[0,1]
	s_waitcnt vmcnt(15)
	v_lshlrev_b32_e32 v230, 16, v154
	v_and_b32_e32 v231, 0xffff0000, v154
	v_pk_add_f32 v[206:207], v[206:207], v[230:231]
	v_pk_fma_f32 v[232:233], v[72:73], v[206:207], v[230:231] op_sel_hi:[0,1,1] neg_lo:[0,0,1] neg_hi:[0,0,1]
	v_cvt_pk_bf16_f32 v218, v232, v233
	v_lshlrev_b32_e32 v230, 16, v155
	v_and_b32_e32 v231, 0xffff0000, v155
	v_pk_add_f32 v[208:209], v[208:209], v[230:231]
	v_pk_fma_f32 v[232:233], v[72:73], v[208:209], v[230:231] op_sel_hi:[0,1,1] neg_lo:[0,0,1] neg_hi:[0,0,1]
	v_cvt_pk_bf16_f32 v219, v232, v233
	v_lshlrev_b32_e32 v230, 16, v156
	v_and_b32_e32 v231, 0xffff0000, v156
	v_pk_add_f32 v[210:211], v[210:211], v[230:231]
	v_pk_fma_f32 v[232:233], v[72:73], v[210:211], v[230:231] op_sel_hi:[0,1,1] neg_lo:[0,0,1] neg_hi:[0,0,1]
	v_cvt_pk_bf16_f32 v220, v232, v233
	v_lshlrev_b32_e32 v230, 16, v157
	v_and_b32_e32 v231, 0xffff0000, v157
	v_pk_add_f32 v[212:213], v[212:213], v[230:231]
	v_pk_fma_f32 v[232:233], v[72:73], v[212:213], v[230:231] op_sel_hi:[0,1,1] neg_lo:[0,0,1] neg_hi:[0,0,1]
	v_cvt_pk_bf16_f32 v221, v232, v233
	s_add_u32 s68, s68, 0x800
	s_addc_u32 s69, s69, 0
	global_store_dwordx4 v82, v[218:221], s[68:69]
	s_cmpk_lg_u32 s40, 0x7f0
	s_cbranch_scc1 .Lpl_w6_nopp7
	v_lshlrev_b32_e32 v222, 16, v154
	v_and_b32_e32 v223, 0xffff0000, v154
	v_lshlrev_b32_e32 v224, 16, v155
	v_and_b32_e32 v225, 0xffff0000, v155
	v_lshlrev_b32_e32 v226, 16, v156
	v_and_b32_e32 v227, 0xffff0000, v156
	v_lshlrev_b32_e32 v228, 16, v157
	v_and_b32_e32 v229, 0xffff0000, v157
	s_add_u32 s70, s70, 0x1000
	s_addc_u32 s71, s71, 0
	global_store_dwordx4 v185, v[222:225], s[70:71]
	global_store_dwordx4 v185, v[226:229], s[70:71] offset:16
.Lpl_w6_nopp7:
	v_cndmask_b32_e64 v129, v150, v142, s[72:73]
	v_lshlrev_b32_e32 v158, 16, v129
	v_and_b32_e32 v159, 0xffff0000, v129
	v_pk_add_f32 v[206:207], v[206:207], v[158:159] neg_lo:[0,1] neg_hi:[0,1]
	v_cndmask_b32_e64 v129, v151, v143, s[72:73]
	v_lshlrev_b32_e32 v158, 16, v129
	v_and_b32_e32 v159, 0xffff0000, v129
	v_pk_add_f32 v[208:209], v[208:209], v[158:159] neg_lo:[0,1] neg_hi:[0,1]
	v_cndmask_b32_e64 v129, v152, v144, s[72:73]
	v_lshlrev_b32_e32 v158, 16, v129
	v_and_b32_e32 v159, 0xffff0000, v129
	v_pk_add_f32 v[210:211], v[210:211], v[158:159] neg_lo:[0,1] neg_hi:[0,1]
	v_cndmask_b32_e64 v129, v153, v145, s[72:73]
	v_lshlrev_b32_e32 v158, 16, v129
	v_and_b32_e32 v159, 0xffff0000, v129
	v_pk_add_f32 v[212:213], v[212:213], v[158:159] neg_lo:[0,1] neg_hi:[0,1]
	s_waitcnt vmcnt(15)
	v_lshlrev_b32_e32 v230, 16, v162
	v_and_b32_e32 v231, 0xffff0000, v162
	v_pk_add_f32 v[206:207], v[206:207], v[230:231]
	v_pk_fma_f32 v[232:233], v[72:73], v[206:207], v[230:231] op_sel_hi:[0,1,1] neg_lo:[0,0,1] neg_hi:[0,0,1]
	v_cvt_pk_bf16_f32 v214, v232, v233
	v_lshlrev_b32_e32 v230, 16, v163
	v_and_b32_e32 v231, 0xffff0000, v163
	v_pk_add_f32 v[208:209], v[208:209], v[230:231]
	v_pk_fma_f32 v[232:233], v[72:73], v[208:209], v[230:231] op_sel_hi:[0,1,1] neg_lo:[0,0,1] neg_hi:[0,0,1]
	v_cvt_pk_bf16_f32 v215, v232, v233
	v_lshlrev_b32_e32 v230, 16, v164
	v_and_b32_e32 v231, 0xffff0000, v164
	v_pk_add_f32 v[210:211], v[210:211], v[230:231]
	v_pk_fma_f32 v[232:233], v[72:73], v[210:211], v[230:231] op_sel_hi:[0,1,1] neg_lo:[0,0,1] neg_hi:[0,0,1]
	v_cvt_pk_bf16_f32 v216, v232, v233
	v_lshlrev_b32_e32 v230, 16, v165
	v_and_b32_e32 v231, 0xffff0000, v165
	v_pk_add_f32 v[212:213], v[212:213], v[230:231]
	v_pk_fma_f32 v[232:233], v[72:73], v[212:213], v[230:231] op_sel_hi:[0,1,1] neg_lo:[0,0,1] neg_hi:[0,0,1]
	v_cvt_pk_bf16_f32 v217, v232, v233
	s_add_u32 s68, s68, 0x800
	s_addc_u32 s69, s69, 0
	global_store_dwordx4 v82, v[214:217], s[68:69]
	s_cmpk_lg_u32 s40, 0x7f0
	s_cbranch_scc1 .Lpl_w6_nopp8
	v_lshlrev_b32_e32 v222, 16, v162
	v_and_b32_e32 v223, 0xffff0000, v162
	v_lshlrev_b32_e32 v224, 16, v163
	v_and_b32_e32 v225, 0xffff0000, v163
	v_lshlrev_b32_e32 v226, 16, v164
	v_and_b32_e32 v227, 0xffff0000, v164
	v_lshlrev_b32_e32 v228, 16, v165
	v_and_b32_e32 v229, 0xffff0000, v165
	s_add_u32 s70, s70, 0x1000
	s_addc_u32 s71, s71, 0
	global_store_dwordx4 v185, v[222:225], s[70:71]
	global_store_dwordx4 v185, v[226:229], s[70:71] offset:16
; __device__ __forceinline__ u32x4 pack8(const float* f) { u32x4 w; w.x = pk2(f[0], f[1]); w.y = pk2(f[2], f[3]); w.z = pk2(f[4], f[5]); w.w = pk2(f[6], f[7]); return w; }
; template <int NTOK, bool SMP>
; __device__ __forceinline__ void mixer_item(const Params& p, int it) {
;     ...
;         for (int t = 0; t < NTOK; ++t) {
;             const int tt = t0 + t; float x[8], y[8], f[8];
;             xpool(tt, x);
;             const float cnt = SMP ? (float)w : (float)min(w, tt + 1); const float ic = 1.0f / cnt;
; #pragma unroll
;             for (int i = 0; i < 8; ++i) { s[i] += x[i]; y[i] = s[i] * ic - x[i]; }
;             *(u32x4*)(yp + (size_t)(seqrow0 + tt) * 1024 + pc) = pack8(y);
;             xpool(tt - w + 1, f);
; #pragma unroll
;             for (int i = 0; i < 8; ++i) s[i] -= f[i];
;             if (SMP) { float* o = p.out + O_PS + ((size_t)sb * 15 + 11 + t) * 1024 + pc; *(f32x4*)o = (f32x4){x[0], x[1], x[2], x[3]}; *(f32x4*)(o + 4) = (f32x4){x[4], x[5], x[6], x[7]}; }
;             else if (tt >= 2033) { float* o = p.out + O_PP + ((size_t)b * 15 + (tt - 2033)) * 1024 + pc; *(f32x4*)o = (f32x4){x[0], x[1], x[2], x[3]}; *(f32x4*)(o + 4) = (f32x4){x[4], x[5], x[6], x[7]}; }
.Lpl_w6_nopp8:
	v_cndmask_b32_e64 v129, v154, v146, s[72:73]
	v_lshlrev_b32_e32 v158, 16, v129
	v_and_b32_e32 v159, 0xffff0000, v129
	v_pk_add_f32 v[206:207], v[206:207], v[158:159] neg_lo:[0,1] neg_hi:[0,1]
	v_cndmask_b32_e64 v129, v155, v147, s[72:73]
	v_lshlrev_b32_e32 v158, 16, v129
	v_and_b32_e32 v159, 0xffff0000, v129
	v_pk_add_f32 v[208:209], v[208:209], v[158:159] neg_lo:[0,1] neg_hi:[0,1]
	v_cndmask_b32_e64 v129, v156, v148, s[72:73]
	v_lshlrev_b32_e32 v158, 16, v129
	v_and_b32_e32 v159, 0xffff0000, v129
	v_pk_add_f32 v[210:211], v[210:211], v[158:159] neg_lo:[0,1] neg_hi:[0,1]
	v_cndmask_b32_e64 v129, v157, v149, s[72:73]
	v_lshlrev_b32_e32 v158, 16, v129
	v_and_b32_e32 v159, 0xffff0000, v129
	v_pk_add_f32 v[212:213], v[212:213], v[158:159] neg_lo:[0,1] neg_hi:[0,1]
	s_waitcnt vmcnt(15)
	v_lshlrev_b32_e32 v230, 16, v176
	v_and_b32_e32 v231, 0xffff0000, v176
	v_pk_add_f32 v[206:207], v[206:207], v[230:231]
	v_pk_fma_f32 v[232:233], v[72:73], v[206:207], v[230:231] op_sel_hi:[0,1,1] neg_lo:[0,0,1] neg_hi:[0,0,1]
	v_cvt_pk_bf16_f32 v218, v232, v233
	v_lshlrev_b32_e32 v230, 16, v177
	v_and_b32_e32 v231, 0xffff0000, v177
	v_pk_add_f32 v[208:209], v[208:209], v[230:231]
	v_pk_fma_f32 v[232:233], v[72:73], v[208:209], v[230:231] op_sel_hi:[0,1,1] neg_lo:[0,0,1] neg_hi:[0,0,1]
	v_cvt_pk_bf16_f32 v219, v232, v233
	v_lshlrev_b32_e32 v230, 16, v178
	v_and_b32_e32 v231, 0xffff0000, v178
	v_pk_add_f32 v[210:211], v[210:211], v[230:231]
	v_pk_fma_f32 v[232:233], v[72:73], v[210:211], v[230:231] op_sel_hi:[0,1,1] neg_lo:[0,0,1] neg_hi:[0,0,1]
	v_cvt_pk_bf16_f32 v220, v232, v233
	v_lshlrev_b32_e32 v230, 16, v179
	v_and_b32_e32 v231, 0xffff0000, v179
	v_pk_add_f32 v[212:213], v[212:213], v[230:231]
	v_pk_fma_f32 v[232:233], v[72:73], v[212:213], v[230:231] op_sel_hi:[0,1,1] neg_lo:[0,0,1] neg_hi:[0,0,1]
	v_cvt_pk_bf16_f32 v221, v232, v233
	s_add_u32 s68, s68, 0x800
	s_addc_u32 s69, s69, 0
	global_store_dwordx4 v82, v[218:221], s[68:69]
	s_cmpk_lg_u32 s40, 0x7f0
	s_cbranch_scc1 .Lpl_w6_nopp9
	v_lshlrev_b32_e32 v222, 16, v176
	v_and_b32_e32 v223, 0xffff0000, v176
	v_lshlrev_b32_e32 v224, 16, v177
	v_and_b32_e32 v225, 0xffff0000, v177
	v_lshlrev_b32_e32 v226, 16, v178
	v_and_b32_e32 v227, 0xffff0000, v178
	v_lshlrev_b32_e32 v228, 16, v179
	v_and_b32_e32 v229, 0xffff0000, v179
	s_add_u32 s70, s70, 0x1000
	s_addc_u32 s71, s71, 0
	global_store_dwordx4 v185, v[222:225], s[70:71]
	global_store_dwordx4 v185, v[226:229], s[70:71] offset:16
.Lpl_w6_nopp9:
	v_cndmask_b32_e64 v129, v162, v150, s[72:73]
	v_lshlrev_b32_e32 v158, 16, v129
	v_and_b32_e32 v159, 0xffff0000, v129
	v_pk_add_f32 v[206:207], v[206:207], v[158:159] neg_lo:[0,1] neg_hi:[0,1]
	v_cndmask_b32_e64 v129, v163, v151, s[72:73]
	v_lshlrev_b32_e32 v158, 16, v129
	v_and_b32_e32 v159, 0xffff0000, v129
	v_pk_add_f32 v[208:209], v[208:209], v[158:159] neg_lo:[0,1] neg_hi:[0,1]
	v_cndmask_b32_e64 v129, v164, v152, s[72:73]
	v_lshlrev_b32_e32 v158, 16, v129
	v_and_b32_e32 v159, 0xffff0000, v129
	v_pk_add_f32 v[210:211], v[210:211], v[158:159] neg_lo:[0,1] neg_hi:[0,1]
	v_cndmask_b32_e64 v129, v165, v153, s[72:73]
	v_lshlrev_b32_e32 v158, 16, v129
	v_and_b32_e32 v159, 0xffff0000, v129
	v_pk_add_f32 v[212:213], v[212:213], v[158:159] neg_lo:[0,1] neg_hi:[0,1]
	s_waitcnt vmcnt(15)
	v_lshlrev_b32_e32 v230, 16, v180
	v_and_b32_e32 v231, 0xffff0000, v180
	v_pk_add_f32 v[206:207], v[206:207], v[230:231]
	v_pk_fma_f32 v[232:233], v[72:73], v[206:207], v[230:231] op_sel_hi:[0,1,1] neg_lo:[0,0,1] neg_hi:[0,0,1]
	v_cvt_pk_bf16_f32 v214, v232, v233
	v_lshlrev_b32_e32 v230, 16, v181
	v_and_b32_e32 v231, 0xffff0000, v181
	v_pk_add_f32 v[208:209], v[208:209], v[230:231]
	v_pk_fma_f32 v[232:233], v[72:73], v[208:209], v[230:231] op_sel_hi:[0,1,1] neg_lo:[0,0,1] neg_hi:[0,0,1]
	v_cvt_pk_bf16_f32 v215, v232, v233
	v_lshlrev_b32_e32 v230, 16, v182
	v_and_b32_e32 v231, 0xffff0000, v182
	v_pk_add_f32 v[210:211], v[210:211], v[230:231]
	v_pk_fma_f32 v[232:233], v[72:73], v[210:211], v[230:231] op_sel_hi:[0,1,1] neg_lo:[0,0,1] neg_hi:[0,0,1]
	v_cvt_pk_bf16_f32 v216, v232, v233
	v_lshlrev_b32_e32 v230, 16, v183
	v_and_b32_e32 v231, 0xffff0000, v183
	v_pk_add_f32 v[212:213], v[212:213], v[230:231]
	v_pk_fma_f32 v[232:233], v[72:73], v[212:213], v[230:231] op_sel_hi:[0,1,1] neg_lo:[0,0,1] neg_hi:[0,0,1]
	v_cvt_pk_bf16_f32 v217, v232, v233
	s_add_u32 s68, s68, 0x800
	s_addc_u32 s69, s69, 0
	global_store_dwordx4 v82, v[214:217], s[68:69]
	s_cmpk_lg_u32 s40, 0x7f0
	s_cbranch_scc1 .Lpl_w6_nopp10
	v_lshlrev_b32_e32 v222, 16, v180
	v_and_b32_e32 v223, 0xffff0000, v180
	v_lshlrev_b32_e32 v224, 16, v181
	v_and_b32_e32 v225, 0xffff0000, v181
	v_lshlrev_b32_e32 v226, 16, v182
	v_and_b32_e32 v227, 0xffff0000, v182
	v_lshlrev_b32_e32 v228, 16, v183
	v_and_b32_e32 v229, 0xffff0000, v183
	s_add_u32 s70, s70, 0x1000
	s_addc_u32 s71, s71, 0
	global_store_dwordx4 v185, v[222:225], s[70:71]
	global_store_dwordx4 v185, v[226:229], s[70:71] offset:16
; __device__ __forceinline__ u32x4 pack8(const float* f) { u32x4 w; w.x = pk2(f[0], f[1]); w.y = pk2(f[2], f[3]); w.z = pk2(f[4], f[5]); w.w = pk2(f[6], f[7]); return w; }
; template <int NTOK, bool SMP>
; __device__ __forceinline__ void mixer_item(const Params& p, int it) {
;     ...
;         for (int t = 0; t < NTOK; ++t) {
;             const int tt = t0 + t; float x[8], y[8], f[8];
;             xpool(tt, x);
;             const float cnt = SMP ? (float)w : (float)min(w, tt + 1); const float ic = 1.0f / cnt;
; #pragma unroll
;             for (int i = 0; i < 8; ++i) { s[i] += x[i]; y[i] = s[i] * ic - x[i]; }
;             *(u32x4*)(yp + (size_t)(seqrow0 + tt) * 1024 + pc) = pack8(y);
;             xpool(tt - w + 1, f);
; #pragma unroll
;             for (int i = 0; i < 8; ++i) s[i] -= f[i];
;             if (SMP) { float* o = p.out + O_PS + ((size_t)sb * 15 + 11 + t) * 1024 + pc; *(f32x4*)o = (f32x4){x[0], x[1], x[2], x[3]}; *(f32x4*)(o + 4) = (f32x4){x[4], x[5], x[6], x[7]}; }
;             else if (tt >= 2033) { float* o = p.out + O_PP + ((size_t)b * 15 + (tt - 2033)) * 1024 + pc; *(f32x4*)o = (f32x4){x[0], x[1], x[2], x[3]}; *(f32x4*)(o + 4) = (f32x4){x[4], x[5], x[6], x[7]}; }
.Lpl_w6_nopp10:
	v_cndmask_b32_e64 v129, v176, v154, s[72:73]
	v_lshlrev_b32_e32 v158, 16, v129
	v_and_b32_e32 v159, 0xffff0000, v129
	v_pk_add_f32 v[206:207], v[206:207], v[158:159] neg_lo:[0,1] neg_hi:[0,1]
	v_cndmask_b32_e64 v129, v177, v155, s[72:73]
	v_lshlrev_b32_e32 v158, 16, v129
	v_and_b32_e32 v159, 0xffff0000, v129
	v_pk_add_f32 v[208:209], v[208:209], v[158:159] neg_lo:[0,1] neg_hi:[0,1]
	v_cndmask_b32_e64 v129, v178, v156, s[72:73]
	v_lshlrev_b32_e32 v158, 16, v129
	v_and_b32_e32 v159, 0xffff0000, v129
	v_pk_add_f32 v[210:211], v[210:211], v[158:159] neg_lo:[0,1] neg_hi:[0,1]
	v_cndmask_b32_e64 v129, v179, v157, s[72:73]
	v_lshlrev_b32_e32 v158, 16, v129
	v_and_b32_e32 v159, 0xffff0000, v129
	v_pk_add_f32 v[212:213], v[212:213], v[158:159] neg_lo:[0,1] neg_hi:[0,1]
	s_waitcnt vmcnt(15)
	v_lshlrev_b32_e32 v230, 16, v186
	v_and_b32_e32 v231, 0xffff0000, v186
	v_pk_add_f32 v[206:207], v[206:207], v[230:231]
	v_pk_fma_f32 v[232:233], v[72:73], v[206:207], v[230:231] op_sel_hi:[0,1,1] neg_lo:[0,0,1] neg_hi:[0,0,1]
	v_cvt_pk_bf16_f32 v218, v232, v233
	v_lshlrev_b32_e32 v230, 16, v187
	v_and_b32_e32 v231, 0xffff0000, v187
	v_pk_add_f32 v[208:209], v[208:209], v[230:231]
	v_pk_fma_f32 v[232:233], v[72:73], v[208:209], v[230:231] op_sel_hi:[0,1,1] neg_lo:[0,0,1] neg_hi:[0,0,1]
	v_cvt_pk_bf16_f32 v219, v232, v233
	v_lshlrev_b32_e32 v230, 16, v188
	v_and_b32_e32 v231, 0xffff0000, v188
	v_pk_add_f32 v[210:211], v[210:211], v[230:231]
	v_pk_fma_f32 v[232:233], v[72:73], v[210:211], v[230:231] op_sel_hi:[0,1,1] neg_lo:[0,0,1] neg_hi:[0,0,1]
	v_cvt_pk_bf16_f32 v220, v232, v233
	v_lshlrev_b32_e32 v230, 16, v189
	v_and_b32_e32 v231, 0xffff0000, v189
	v_pk_add_f32 v[212:213], v[212:213], v[230:231]
	v_pk_fma_f32 v[232:233], v[72:73], v[212:213], v[230:231] op_sel_hi:[0,1,1] neg_lo:[0,0,1] neg_hi:[0,0,1]
	v_cvt_pk_bf16_f32 v221, v232, v233
	s_add_u32 s68, s68, 0x800
	s_addc_u32 s69, s69, 0
	global_store_dwordx4 v82, v[218:221], s[68:69]
	s_cmpk_lg_u32 s40, 0x7f0
	s_cbranch_scc1 .Lpl_w6_nopp11
	v_lshlrev_b32_e32 v222, 16, v186
	v_and_b32_e32 v223, 0xffff0000, v186
	v_lshlrev_b32_e32 v224, 16, v187
	v_and_b32_e32 v225, 0xffff0000, v187
	v_lshlrev_b32_e32 v226, 16, v188
	v_and_b32_e32 v227, 0xffff0000, v188
	v_lshlrev_b32_e32 v228, 16, v189
	v_and_b32_e32 v229, 0xffff0000, v189
	s_add_u32 s70, s70, 0x1000
	s_addc_u32 s71, s71, 0
	global_store_dwordx4 v185, v[222:225], s[70:71]
	global_store_dwordx4 v185, v[226:229], s[70:71] offset:16
.Lpl_w6_nopp11:
	v_cndmask_b32_e64 v129, v180, v162, s[72:73]
	v_lshlrev_b32_e32 v158, 16, v129
	v_and_b32_e32 v159, 0xffff0000, v129
	v_pk_add_f32 v[206:207], v[206:207], v[158:159] neg_lo:[0,1] neg_hi:[0,1]
	v_cndmask_b32_e64 v129, v181, v163, s[72:73]
	v_lshlrev_b32_e32 v158, 16, v129
	v_and_b32_e32 v159, 0xffff0000, v129
	v_pk_add_f32 v[208:209], v[208:209], v[158:159] neg_lo:[0,1] neg_hi:[0,1]
	v_cndmask_b32_e64 v129, v182, v164, s[72:73]
	v_lshlrev_b32_e32 v158, 16, v129
	v_and_b32_e32 v159, 0xffff0000, v129
	v_pk_add_f32 v[210:211], v[210:211], v[158:159] neg_lo:[0,1] neg_hi:[0,1]
	v_cndmask_b32_e64 v129, v183, v165, s[72:73]
	v_lshlrev_b32_e32 v158, 16, v129
	v_and_b32_e32 v159, 0xffff0000, v129
	v_pk_add_f32 v[212:213], v[212:213], v[158:159] neg_lo:[0,1] neg_hi:[0,1]
	s_waitcnt vmcnt(15)
	v_lshlrev_b32_e32 v230, 16, v190
	v_and_b32_e32 v231, 0xffff0000, v190
	v_pk_add_f32 v[206:207], v[206:207], v[230:231]
	v_pk_fma_f32 v[232:233], v[72:73], v[206:207], v[230:231] op_sel_hi:[0,1,1] neg_lo:[0,0,1] neg_hi:[0,0,1]
	v_cvt_pk_bf16_f32 v214, v232, v233
	v_lshlrev_b32_e32 v230, 16, v191
	v_and_b32_e32 v231, 0xffff0000, v191
	v_pk_add_f32 v[208:209], v[208:209], v[230:231]
	v_pk_fma_f32 v[232:233], v[72:73], v[208:209], v[230:231] op_sel_hi:[0,1,1] neg_lo:[0,0,1] neg_hi:[0,0,1]
	v_cvt_pk_bf16_f32 v215, v232, v233
	v_lshlrev_b32_e32 v230, 16, v192
	v_and_b32_e32 v231, 0xffff0000, v192
	v_pk_add_f32 v[210:211], v[210:211], v[230:231]
	v_pk_fma_f32 v[232:233], v[72:73], v[210:211], v[230:231] op_sel_hi:[0,1,1] neg_lo:[0,0,1] neg_hi:[0,0,1]
	v_cvt_pk_bf16_f32 v216, v232, v233
	v_lshlrev_b32_e32 v230, 16, v193
	v_and_b32_e32 v231, 0xffff0000, v193
	v_pk_add_f32 v[212:213], v[212:213], v[230:231]
	v_pk_fma_f32 v[232:233], v[72:73], v[212:213], v[230:231] op_sel_hi:[0,1,1] neg_lo:[0,0,1] neg_hi:[0,0,1]
	v_cvt_pk_bf16_f32 v217, v232, v233
	s_add_u32 s68, s68, 0x800
	s_addc_u32 s69, s69, 0
	global_store_dwordx4 v82, v[214:217], s[68:69]
	s_cmpk_lg_u32 s40, 0x7f0
	s_cbranch_scc1 .Lpl_w6_nopp12
	v_lshlrev_b32_e32 v222, 16, v190
	v_and_b32_e32 v223, 0xffff0000, v190
	v_lshlrev_b32_e32 v224, 16, v191
	v_and_b32_e32 v225, 0xffff0000, v191
	v_lshlrev_b32_e32 v226, 16, v192
	v_and_b32_e32 v227, 0xffff0000, v192
	v_lshlrev_b32_e32 v228, 16, v193
	v_and_b32_e32 v229, 0xffff0000, v193
	s_add_u32 s70, s70, 0x1000
	s_addc_u32 s71, s71, 0
	global_store_dwordx4 v185, v[222:225], s[70:71]
	global_store_dwordx4 v185, v[226:229], s[70:71] offset:16
; __device__ __forceinline__ u32x4 pack8(const float* f) { u32x4 w; w.x = pk2(f[0], f[1]); w.y = pk2(f[2], f[3]); w.z = pk2(f[4], f[5]); w.w = pk2(f[6], f[7]); return w; }
; template <int NTOK, bool SMP>
; __device__ __forceinline__ void mixer_item(const Params& p, int it) {
;     ...
;         for (int t = 0; t < NTOK; ++t) {
;             const int tt = t0 + t; float x[8], y[8], f[8];
;             xpool(tt, x);
;             const float cnt = SMP ? (float)w : (float)min(w, tt + 1); const float ic = 1.0f / cnt;
; #pragma unroll
;             for (int i = 0; i < 8; ++i) { s[i] += x[i]; y[i] = s[i] * ic - x[i]; }
;             *(u32x4*)(yp + (size_t)(seqrow0 + tt) * 1024 + pc) = pack8(y);
;             xpool(tt - w + 1, f);
; #pragma unroll
;             for (int i = 0; i < 8; ++i) s[i] -= f[i];
;             if (SMP) { float* o = p.out + O_PS + ((size_t)sb * 15 + 11 + t) * 1024 + pc; *(f32x4*)o = (f32x4){x[0], x[1], x[2], x[3]}; *(f32x4*)(o + 4) = (f32x4){x[4], x[5], x[6], x[7]}; }
;             else if (tt >= 2033) { float* o = p.out + O_PP + ((size_t)b * 15 + (tt - 2033)) * 1024 + pc; *(f32x4*)o = (f32x4){x[0], x[1], x[2], x[3]}; *(f32x4*)(o + 4) = (f32x4){x[4], x[5], x[6], x[7]}; }
.Lpl_w6_nopp12:
	v_cndmask_b32_e64 v129, v186, v176, s[72:73]
	v_lshlrev_b32_e32 v158, 16, v129
	v_and_b32_e32 v159, 0xffff0000, v129
	v_pk_add_f32 v[206:207], v[206:207], v[158:159] neg_lo:[0,1] neg_hi:[0,1]
	v_cndmask_b32_e64 v129, v187, v177, s[72:73]
	v_lshlrev_b32_e32 v158, 16, v129
	v_and_b32_e32 v159, 0xffff0000, v129
	v_pk_add_f32 v[208:209], v[208:209], v[158:159] neg_lo:[0,1] neg_hi:[0,1]
	v_cndmask_b32_e64 v129, v188, v178, s[72:73]
	v_lshlrev_b32_e32 v158, 16, v129
	v_and_b32_e32 v159, 0xffff0000, v129
	v_pk_add_f32 v[210:211], v[210:211], v[158:159] neg_lo:[0,1] neg_hi:[0,1]
	v_cndmask_b32_e64 v129, v189, v179, s[72:73]
	v_lshlrev_b32_e32 v158, 16, v129
	v_and_b32_e32 v159, 0xffff0000, v129
	v_pk_add_f32 v[212:213], v[212:213], v[158:159] neg_lo:[0,1] neg_hi:[0,1]
	s_waitcnt vmcnt(15)
	v_lshlrev_b32_e32 v230, 16, v194
	v_and_b32_e32 v231, 0xffff0000, v194
	v_pk_add_f32 v[206:207], v[206:207], v[230:231]
	v_pk_fma_f32 v[232:233], v[72:73], v[206:207], v[230:231] op_sel_hi:[0,1,1] neg_lo:[0,0,1] neg_hi:[0,0,1]
	v_cvt_pk_bf16_f32 v218, v232, v233
	v_lshlrev_b32_e32 v230, 16, v195
	v_and_b32_e32 v231, 0xffff0000, v195
	v_pk_add_f32 v[208:209], v[208:209], v[230:231]
	v_pk_fma_f32 v[232:233], v[72:73], v[208:209], v[230:231] op_sel_hi:[0,1,1] neg_lo:[0,0,1] neg_hi:[0,0,1]
	v_cvt_pk_bf16_f32 v219, v232, v233
	v_lshlrev_b32_e32 v230, 16, v196
	v_and_b32_e32 v231, 0xffff0000, v196
	v_pk_add_f32 v[210:211], v[210:211], v[230:231]
	v_pk_fma_f32 v[232:233], v[72:73], v[210:211], v[230:231] op_sel_hi:[0,1,1] neg_lo:[0,0,1] neg_hi:[0,0,1]
	v_cvt_pk_bf16_f32 v220, v232, v233
	v_lshlrev_b32_e32 v230, 16, v197
	v_and_b32_e32 v231, 0xffff0000, v197
	v_pk_add_f32 v[212:213], v[212:213], v[230:231]
	v_pk_fma_f32 v[232:233], v[72:73], v[212:213], v[230:231] op_sel_hi:[0,1,1] neg_lo:[0,0,1] neg_hi:[0,0,1]
	v_cvt_pk_bf16_f32 v221, v232, v233
	s_add_u32 s68, s68, 0x800
	s_addc_u32 s69, s69, 0
	global_store_dwordx4 v82, v[218:221], s[68:69]
	s_cmpk_lg_u32 s40, 0x7f0
	s_cbranch_scc1 .Lpl_w6_nopp13
	v_lshlrev_b32_e32 v222, 16, v194
	v_and_b32_e32 v223, 0xffff0000, v194
	v_lshlrev_b32_e32 v224, 16, v195
	v_and_b32_e32 v225, 0xffff0000, v195
	v_lshlrev_b32_e32 v226, 16, v196
	v_and_b32_e32 v227, 0xffff0000, v196
	v_lshlrev_b32_e32 v228, 16, v197
	v_and_b32_e32 v229, 0xffff0000, v197
	s_add_u32 s70, s70, 0x1000
	s_addc_u32 s71, s71, 0
	global_store_dwordx4 v185, v[222:225], s[70:71]
	global_store_dwordx4 v185, v[226:229], s[70:71] offset:16
.Lpl_w6_nopp13:
	v_cndmask_b32_e64 v129, v190, v180, s[72:73]
	v_lshlrev_b32_e32 v158, 16, v129
	v_and_b32_e32 v159, 0xffff0000, v129
	v_pk_add_f32 v[206:207], v[206:207], v[158:159] neg_lo:[0,1] neg_hi:[0,1]
	v_cndmask_b32_e64 v129, v191, v181, s[72:73]
	v_lshlrev_b32_e32 v158, 16, v129
	v_and_b32_e32 v159, 0xffff0000, v129
	v_pk_add_f32 v[208:209], v[208:209], v[158:159] neg_lo:[0,1] neg_hi:[0,1]
	v_cndmask_b32_e64 v129, v192, v182, s[72:73]
	v_lshlrev_b32_e32 v158, 16, v129
	v_and_b32_e32 v159, 0xffff0000, v129
	v_pk_add_f32 v[210:211], v[210:211], v[158:159] neg_lo:[0,1] neg_hi:[0,1]
	v_cndmask_b32_e64 v129, v193, v183, s[72:73]
	v_lshlrev_b32_e32 v158, 16, v129
	v_and_b32_e32 v159, 0xffff0000, v129
	v_pk_add_f32 v[212:213], v[212:213], v[158:159] neg_lo:[0,1] neg_hi:[0,1]
	s_waitcnt vmcnt(15)
	v_lshlrev_b32_e32 v230, 16, v198
	v_and_b32_e32 v231, 0xffff0000, v198
	v_pk_add_f32 v[206:207], v[206:207], v[230:231]
	v_pk_fma_f32 v[232:233], v[72:73], v[206:207], v[230:231] op_sel_hi:[0,1,1] neg_lo:[0,0,1] neg_hi:[0,0,1]
	v_cvt_pk_bf16_f32 v214, v232, v233
	v_lshlrev_b32_e32 v230, 16, v199
	v_and_b32_e32 v231, 0xffff0000, v199
	v_pk_add_f32 v[208:209], v[208:209], v[230:231]
	v_pk_fma_f32 v[232:233], v[72:73], v[208:209], v[230:231] op_sel_hi:[0,1,1] neg_lo:[0,0,1] neg_hi:[0,0,1]
	v_cvt_pk_bf16_f32 v215, v232, v233
	v_lshlrev_b32_e32 v230, 16, v200
	v_and_b32_e32 v231, 0xffff0000, v200
	v_pk_add_f32 v[210:211], v[210:211], v[230:231]
	v_pk_fma_f32 v[232:233], v[72:73], v[210:211], v[230:231] op_sel_hi:[0,1,1] neg_lo:[0,0,1] neg_hi:[0,0,1]
	v_cvt_pk_bf16_f32 v216, v232, v233
	v_lshlrev_b32_e32 v230, 16, v201
	v_and_b32_e32 v231, 0xffff0000, v201
	v_pk_add_f32 v[212:213], v[212:213], v[230:231]
	v_pk_fma_f32 v[232:233], v[72:73], v[212:213], v[230:231] op_sel_hi:[0,1,1] neg_lo:[0,0,1] neg_hi:[0,0,1]
	v_cvt_pk_bf16_f32 v217, v232, v233
	s_add_u32 s68, s68, 0x800
	s_addc_u32 s69, s69, 0
	global_store_dwordx4 v82, v[214:217], s[68:69]
	s_cmpk_lg_u32 s40, 0x7f0
	s_cbranch_scc1 .Lpl_w6_nopp14
	v_lshlrev_b32_e32 v222, 16, v198
	v_and_b32_e32 v223, 0xffff0000, v198
	v_lshlrev_b32_e32 v224, 16, v199
	v_and_b32_e32 v225, 0xffff0000, v199
	v_lshlrev_b32_e32 v226, 16, v200
	v_and_b32_e32 v227, 0xffff0000, v200
	v_lshlrev_b32_e32 v228, 16, v201
	v_and_b32_e32 v229, 0xffff0000, v201
	s_add_u32 s70, s70, 0x1000
	s_addc_u32 s71, s71, 0
	global_store_dwordx4 v185, v[222:225], s[70:71]
	global_store_dwordx4 v185, v[226:229], s[70:71] offset:16
; __device__ __forceinline__ u32x4 pack8(const float* f) { u32x4 w; w.x = pk2(f[0], f[1]); w.y = pk2(f[2], f[3]); w.z = pk2(f[4], f[5]); w.w = pk2(f[6], f[7]); return w; }
; template <int NTOK, bool SMP>
; __device__ __forceinline__ void mixer_item(const Params& p, int it) {
;     ...
;         for (int q = 1; q < 16; ++q) if (q < w) { float f[8]; xpool(t0 - q, f);
; #pragma unroll
;             for (int i = 0; i < 8; ++i) s[i] += f[i]; }
;     ...
;         for (int t = 0; t < NTOK; ++t) {
;             const int tt = t0 + t; float x[8], y[8], f[8];
;             xpool(tt, x);
;             const float cnt = SMP ? (float)w : (float)min(w, tt + 1); const float ic = 1.0f / cnt;
; #pragma unroll
;             for (int i = 0; i < 8; ++i) { s[i] += x[i]; y[i] = s[i] * ic - x[i]; }
;             *(u32x4*)(yp + (size_t)(seqrow0 + tt) * 1024 + pc) = pack8(y);
;             xpool(tt - w + 1, f);
; #pragma unroll
;             for (int i = 0; i < 8; ++i) s[i] -= f[i];
;             if (SMP) { float* o = p.out + O_PS + ((size_t)sb * 15 + 11 + t) * 1024 + pc; *(f32x4*)o = (f32x4){x[0], x[1], x[2], x[3]}; *(f32x4*)(o + 4) = (f32x4){x[4], x[5], x[6], x[7]}; }
;             else if (tt >= 2033) { float* o = p.out + O_PP + ((size_t)b * 15 + (tt - 2033)) * 1024 + pc; *(f32x4*)o = (f32x4){x[0], x[1], x[2], x[3]}; *(f32x4*)(o + 4) = (f32x4){x[4], x[5], x[6], x[7]}; }
.Lpl_w6_nopp14:
	v_cndmask_b32_e64 v129, v194, v186, s[72:73]
	v_lshlrev_b32_e32 v158, 16, v129
	v_and_b32_e32 v159, 0xffff0000, v129
	v_pk_add_f32 v[206:207], v[206:207], v[158:159] neg_lo:[0,1] neg_hi:[0,1]
	v_cndmask_b32_e64 v129, v195, v187, s[72:73]
	v_lshlrev_b32_e32 v158, 16, v129
	v_and_b32_e32 v159, 0xffff0000, v129
	v_pk_add_f32 v[208:209], v[208:209], v[158:159] neg_lo:[0,1] neg_hi:[0,1]
	v_cndmask_b32_e64 v129, v196, v188, s[72:73]
	v_lshlrev_b32_e32 v158, 16, v129
	v_and_b32_e32 v159, 0xffff0000, v129
	v_pk_add_f32 v[210:211], v[210:211], v[158:159] neg_lo:[0,1] neg_hi:[0,1]
	v_cndmask_b32_e64 v129, v197, v189, s[72:73]
	v_lshlrev_b32_e32 v158, 16, v129
	v_and_b32_e32 v159, 0xffff0000, v129
	v_pk_add_f32 v[212:213], v[212:213], v[158:159] neg_lo:[0,1] neg_hi:[0,1]
	s_waitcnt vmcnt(15)
	v_lshlrev_b32_e32 v230, 16, v202
	v_and_b32_e32 v231, 0xffff0000, v202
	v_pk_add_f32 v[206:207], v[206:207], v[230:231]
	v_pk_fma_f32 v[232:233], v[72:73], v[206:207], v[230:231] op_sel_hi:[0,1,1] neg_lo:[0,0,1] neg_hi:[0,0,1]
	v_cvt_pk_bf16_f32 v218, v232, v233
	v_lshlrev_b32_e32 v230, 16, v203
	v_and_b32_e32 v231, 0xffff0000, v203
	v_pk_add_f32 v[208:209], v[208:209], v[230:231]
	v_pk_fma_f32 v[232:233], v[72:73], v[208:209], v[230:231] op_sel_hi:[0,1,1] neg_lo:[0,0,1] neg_hi:[0,0,1]
	v_cvt_pk_bf16_f32 v219, v232, v233
	v_lshlrev_b32_e32 v230, 16, v204
	v_and_b32_e32 v231, 0xffff0000, v204
	v_pk_add_f32 v[210:211], v[210:211], v[230:231]
	v_pk_fma_f32 v[232:233], v[72:73], v[210:211], v[230:231] op_sel_hi:[0,1,1] neg_lo:[0,0,1] neg_hi:[0,0,1]
	v_cvt_pk_bf16_f32 v220, v232, v233
	v_lshlrev_b32_e32 v230, 16, v205
	v_and_b32_e32 v231, 0xffff0000, v205
	v_pk_add_f32 v[212:213], v[212:213], v[230:231]
	v_pk_fma_f32 v[232:233], v[72:73], v[212:213], v[230:231] op_sel_hi:[0,1,1] neg_lo:[0,0,1] neg_hi:[0,0,1]
	v_cvt_pk_bf16_f32 v221, v232, v233
	s_add_u32 s68, s68, 0x800
	s_addc_u32 s69, s69, 0
	global_store_dwordx4 v82, v[218:221], s[68:69]
	s_cmpk_lg_u32 s40, 0x7f0
	s_cbranch_scc1 .Lpl_w6_nopp15
	v_lshlrev_b32_e32 v222, 16, v202
	v_and_b32_e32 v223, 0xffff0000, v202
	v_lshlrev_b32_e32 v224, 16, v203
	v_and_b32_e32 v225, 0xffff0000, v203
	v_lshlrev_b32_e32 v226, 16, v204
	v_and_b32_e32 v227, 0xffff0000, v204
	v_lshlrev_b32_e32 v228, 16, v205
	v_and_b32_e32 v229, 0xffff0000, v205
	s_add_u32 s70, s70, 0x1000
	s_addc_u32 s71, s71, 0
	global_store_dwordx4 v185, v[222:225], s[70:71]
	global_store_dwordx4 v185, v[226:229], s[70:71] offset:16
.Lpl_w6_nopp15:
	s_branch .Lpl_done
.Lpl_w7:
	s_mul_i32 s64, s60, 0x4a00
	s_mul_hi_u32 s65, s60, 0x4a00
	s_add_u32 s64, s64, s30
	s_addc_u32 s65, s65, s31
	s_add_u32 s64, s64, 0x2000
	s_addc_u32 s65, s65, 0
	s_mov_b32 s72, 0
	s_mov_b32 s73, -1
	s_mov_b64 s[76:77], exec
	s_cmp_eq_u32 s40, 0
	s_cselect_b64 s[78:79], -1, 0
	s_cbranch_scc1 .Lpl_w7_zeroP
	s_mov_b64 s[66:67], s[64:65]
	s_sub_u32 s66, s66, 0x4a00
	s_subb_u32 s67, s67, 0
	global_load_dwordx4 v[56:59], v82, s[66:67]
	s_sub_u32 s66, s66, 0x4a00
	s_subb_u32 s67, s67, 0
	global_load_dwordx4 v[52:55], v82, s[66:67]
	s_sub_u32 s66, s66, 0x4a00
	s_subb_u32 s67, s67, 0
	global_load_dwordx4 v[48:51], v82, s[66:67]
	s_sub_u32 s66, s66, 0x4a00
	s_subb_u32 s67, s67, 0
	global_load_dwordx4 v[44:47], v82, s[66:67]
	s_sub_u32 s66, s66, 0x4a00
	s_subb_u32 s67, s67, 0
	global_load_dwordx4 v[40:43], v82, s[66:67]
	s_sub_u32 s66, s66, 0x4a00
	s_subb_u32 s67, s67, 0
	global_load_dwordx4 v[36:39], v82, s[66:67]
	s_sub_u32 s66, s66, 0x4a00
	s_subb_u32 s67, s67, 0
	global_load_dwordx4 v[32:35], v82, s[66:67]
	s_sub_u32 s66, s66, 0x4a00
	s_subb_u32 s67, s67, 0
	global_load_dwordx4 v[28:31], v82, s[66:67]
	s_sub_u32 s66, s66, 0x4a00
	s_subb_u32 s67, s67, 0
	global_load_dwordx4 v[24:27], v82, s[66:67]
	s_sub_u32 s66, s66, 0x4a00
	s_subb_u32 s67, s67, 0
	global_load_dwordx4 v[20:23], v82, s[66:67]
	s_sub_u32 s66, s66, 0x4a00
	s_subb_u32 s67, s67, 0
	global_load_dwordx4 v[16:19], v82, s[66:67]
	s_sub_u32 s66, s66, 0x4a00
	s_subb_u32 s67, s67, 0
	global_load_dwordx4 v[12:15], v82, s[66:67]
	s_sub_u32 s66, s66, 0x4a00
	s_subb_u32 s67, s67, 0
	global_load_dwordx4 v[8:11], v82, s[66:67]
	s_sub_u32 s66, s66, 0x4a00
	s_subb_u32 s67, s67, 0
	global_load_dwordx4 v[4:7], v82, s[66:67]
	s_sub_u32 s66, s66, 0x4a00
	s_subb_u32 s67, s67, 0
	global_load_dwordx4 v[0:3], v82, s[66:67]
	s_branch .Lpl_w7_loadX
.Lpl_w7_zeroP:
	v_mov_b32_e32 v56, 0
	v_mov_b32_e32 v57, 0
	v_mov_b32_e32 v58, 0
	v_mov_b32_e32 v59, 0
	v_mov_b32_e32 v52, 0
	v_mov_b32_e32 v53, 0
	v_mov_b32_e32 v54, 0
	v_mov_b32_e32 v55, 0
	v_mov_b32_e32 v48, 0
	v_mov_b32_e32 v49, 0
	v_mov_b32_e32 v50, 0
	v_mov_b32_e32 v51, 0
	v_mov_b32_e32 v44, 0
	v_mov_b32_e32 v45, 0
	v_mov_b32_e32 v46, 0
	v_mov_b32_e32 v47, 0
	v_mov_b32_e32 v40, 0
	v_mov_b32_e32 v41, 0
	v_mov_b32_e32 v42, 0
	v_mov_b32_e32 v43, 0
	v_mov_b32_e32 v36, 0
	v_mov_b32_e32 v37, 0
	v_mov_b32_e32 v38, 0
	v_mov_b32_e32 v39, 0
	v_mov_b32_e32 v32, 0
	v_mov_b32_e32 v33, 0
	v_mov_b32_e32 v34, 0
	v_mov_b32_e32 v35, 0
	v_mov_b32_e32 v28, 0
	v_mov_b32_e32 v29, 0
	v_mov_b32_e32 v30, 0
	v_mov_b32_e32 v31, 0
	v_mov_b32_e32 v24, 0
	v_mov_b32_e32 v25, 0
	v_mov_b32_e32 v26, 0
	v_mov_b32_e32 v27, 0
	v_mov_b32_e32 v20, 0
	v_mov_b32_e32 v21, 0
	v_mov_b32_e32 v22, 0
	v_mov_b32_e32 v23, 0
	v_mov_b32_e32 v16, 0
	v_mov_b32_e32 v17, 0
	v_mov_b32_e32 v18, 0
	v_mov_b32_e32 v19, 0
	v_mov_b32_e32 v12, 0
	v_mov_b32_e32 v13, 0
	v_mov_b32_e32 v14, 0
	v_mov_b32_e32 v15, 0
	v_mov_b32_e32 v8, 0
	v_mov_b32_e32 v9, 0
	v_mov_b32_e32 v10, 0
	v_mov_b32_e32 v11, 0
	v_mov_b32_e32 v4, 0
	v_mov_b32_e32 v5, 0
	v_mov_b32_e32 v6, 0
	v_mov_b32_e32 v7, 0
	v_mov_b32_e32 v0, 0
	v_mov_b32_e32 v1, 0
	v_mov_b32_e32 v2, 0
	v_mov_b32_e32 v3, 0
; template <int NTOK, bool SMP>
; __device__ __forceinline__ void mixer_item(const Params& p, int it) {
;     ...
;         for (int q = 1; q < 16; ++q) if (q < w) { float f[8]; xpool(t0 - q, f);
; #pragma unroll
;             for (int i = 0; i < 8; ++i) s[i] += f[i]; }
;     ...
;         for (int t = 0; t < NTOK; ++t) {
;             const int tt = t0 + t; float x[8], y[8], f[8];
;             xpool(tt, x);
.Lpl_w7_loadX:
	s_mov_b64 s[66:67], s[64:65]
	global_load_dwordx4 v[60:63], v82, s[66:67]
	s_add_u32 s66, s66, 0x4a00
	s_addc_u32 s67, s67, 0
	global_load_dwordx4 v[130:133], v82, s[66:67]
	s_add_u32 s66, s66, 0x4a00
	s_addc_u32 s67, s67, 0
	global_load_dwordx4 v[134:137], v82, s[66:67]
	s_add_u32 s66, s66, 0x4a00
	s_addc_u32 s67, s67, 0
	global_load_dwordx4 v[138:141], v82, s[66:67]
	s_add_u32 s66, s66, 0x4a00
	s_addc_u32 s67, s67, 0
	global_load_dwordx4 v[142:145], v82, s[66:67]
	s_add_u32 s66, s66, 0x4a00
	s_addc_u32 s67, s67, 0
	global_load_dwordx4 v[146:149], v82, s[66:67]
	s_add_u32 s66, s66, 0x4a00
	s_addc_u32 s67, s67, 0
	global_load_dwordx4 v[150:153], v82, s[66:67]
	s_add_u32 s66, s66, 0x4a00
	s_addc_u32 s67, s67, 0
	global_load_dwordx4 v[154:157], v82, s[66:67]
	s_add_u32 s66, s66, 0x4a00
	s_addc_u32 s67, s67, 0
	global_load_dwordx4 v[162:165], v82, s[66:67]
	s_add_u32 s66, s66, 0x4a00
	s_addc_u32 s67, s67, 0
	global_load_dwordx4 v[176:179], v82, s[66:67]
	s_add_u32 s66, s66, 0x4a00
	s_addc_u32 s67, s67, 0
	global_load_dwordx4 v[180:183], v82, s[66:67]
	s_add_u32 s66, s66, 0x4a00
	s_addc_u32 s67, s67, 0
	global_load_dwordx4 v[186:189], v82, s[66:67]
	s_add_u32 s66, s66, 0x4a00
	s_addc_u32 s67, s67, 0
	global_load_dwordx4 v[190:193], v82, s[66:67]
	s_add_u32 s66, s66, 0x4a00
	s_addc_u32 s67, s67, 0
	global_load_dwordx4 v[194:197], v82, s[66:67]
	s_add_u32 s66, s66, 0x4a00
	s_addc_u32 s67, s67, 0
	global_load_dwordx4 v[198:201], v82, s[66:67]
	s_add_u32 s66, s66, 0x4a00
	s_addc_u32 s67, s67, 0
	global_load_dwordx4 v[202:205], v82, s[66:67]
	s_lshl_b32 s68, s60, 11
	s_add_u32 s68, s68, s26
	s_addc_u32 s69, s27, 0
	s_add_u32 s68, s68, 0xd439000
	s_addc_u32 s69, s69, 0
	s_mul_i32 s70, s91, 15
	s_add_i32 s70, s70, -1
	s_ashr_i32 s71, s70, 31
	s_lshl_b64 s[70:71], s[70:71], 12
	s_add_u32 s70, s70, s24
	s_addc_u32 s71, s71, s25
	s_add_u32 s70, s70, 0x4624000
	s_addc_u32 s71, s71, 0
	v_lshlrev_b32_e32 v185, 1, v82
	s_waitcnt vmcnt(30)
	v_lshlrev_b32_e32 v230, 16, v56
	v_and_b32_e32 v231, 0xffff0000, v56
	v_pk_add_f32 v[206:207], v[230:231], 0 op_sel_hi:[1,0]
	v_lshlrev_b32_e32 v230, 16, v57
	v_and_b32_e32 v231, 0xffff0000, v57
	v_pk_add_f32 v[208:209], v[230:231], 0 op_sel_hi:[1,0]
	v_lshlrev_b32_e32 v230, 16, v58
	v_and_b32_e32 v231, 0xffff0000, v58
	v_pk_add_f32 v[210:211], v[230:231], 0 op_sel_hi:[1,0]
	v_lshlrev_b32_e32 v230, 16, v59
	v_and_b32_e32 v231, 0xffff0000, v59
	v_pk_add_f32 v[212:213], v[230:231], 0 op_sel_hi:[1,0]
	s_waitcnt vmcnt(29)
	v_lshlrev_b32_e32 v230, 16, v52
	v_and_b32_e32 v231, 0xffff0000, v52
	v_pk_add_f32 v[206:207], v[206:207], v[230:231]
	v_lshlrev_b32_e32 v230, 16, v53
	v_and_b32_e32 v231, 0xffff0000, v53
	v_pk_add_f32 v[208:209], v[208:209], v[230:231]
	v_lshlrev_b32_e32 v230, 16, v54
	v_and_b32_e32 v231, 0xffff0000, v54
	v_pk_add_f32 v[210:211], v[210:211], v[230:231]
	v_lshlrev_b32_e32 v230, 16, v55
	v_and_b32_e32 v231, 0xffff0000, v55
	v_pk_add_f32 v[212:213], v[212:213], v[230:231]
	s_waitcnt vmcnt(28)
	v_lshlrev_b32_e32 v230, 16, v48
	v_and_b32_e32 v231, 0xffff0000, v48
	v_pk_add_f32 v[206:207], v[206:207], v[230:231]
	v_lshlrev_b32_e32 v230, 16, v49
	v_and_b32_e32 v231, 0xffff0000, v49
	v_pk_add_f32 v[208:209], v[208:209], v[230:231]
	v_lshlrev_b32_e32 v230, 16, v50
	v_and_b32_e32 v231, 0xffff0000, v50
	v_pk_add_f32 v[210:211], v[210:211], v[230:231]
	v_lshlrev_b32_e32 v230, 16, v51
	v_and_b32_e32 v231, 0xffff0000, v51
	v_pk_add_f32 v[212:213], v[212:213], v[230:231]
	s_waitcnt vmcnt(27)
	v_lshlrev_b32_e32 v230, 16, v44
	v_and_b32_e32 v231, 0xffff0000, v44
	v_pk_add_f32 v[206:207], v[206:207], v[230:231]
	v_lshlrev_b32_e32 v230, 16, v45
	v_and_b32_e32 v231, 0xffff0000, v45
	v_pk_add_f32 v[208:209], v[208:209], v[230:231]
	v_lshlrev_b32_e32 v230, 16, v46
	v_and_b32_e32 v231, 0xffff0000, v46
	v_pk_add_f32 v[210:211], v[210:211], v[230:231]
	v_lshlrev_b32_e32 v230, 16, v47
	v_and_b32_e32 v231, 0xffff0000, v47
	v_pk_add_f32 v[212:213], v[212:213], v[230:231]
	s_waitcnt vmcnt(26)
	v_lshlrev_b32_e32 v230, 16, v40
	v_and_b32_e32 v231, 0xffff0000, v40
	v_pk_add_f32 v[206:207], v[206:207], v[230:231]
	v_lshlrev_b32_e32 v230, 16, v41
	v_and_b32_e32 v231, 0xffff0000, v41
	v_pk_add_f32 v[208:209], v[208:209], v[230:231]
	v_lshlrev_b32_e32 v230, 16, v42
	v_and_b32_e32 v231, 0xffff0000, v42
	v_pk_add_f32 v[210:211], v[210:211], v[230:231]
	v_lshlrev_b32_e32 v230, 16, v43
	v_and_b32_e32 v231, 0xffff0000, v43
	v_pk_add_f32 v[212:213], v[212:213], v[230:231]
	s_waitcnt vmcnt(25)
	v_lshlrev_b32_e32 v230, 16, v36
	v_and_b32_e32 v231, 0xffff0000, v36
	v_pk_add_f32 v[206:207], v[206:207], v[230:231]
	v_lshlrev_b32_e32 v230, 16, v37
	v_and_b32_e32 v231, 0xffff0000, v37
	v_pk_add_f32 v[208:209], v[208:209], v[230:231]
	v_lshlrev_b32_e32 v230, 16, v38
	v_and_b32_e32 v231, 0xffff0000, v38
	v_pk_add_f32 v[210:211], v[210:211], v[230:231]
	v_lshlrev_b32_e32 v230, 16, v39
	v_and_b32_e32 v231, 0xffff0000, v39
	v_pk_add_f32 v[212:213], v[212:213], v[230:231]
	s_waitcnt vmcnt(24)
	v_lshlrev_b32_e32 v230, 16, v32
	v_and_b32_e32 v231, 0xffff0000, v32
	v_pk_add_f32 v[206:207], v[206:207], v[230:231]
	v_lshlrev_b32_e32 v230, 16, v33
	v_and_b32_e32 v231, 0xffff0000, v33
	v_pk_add_f32 v[208:209], v[208:209], v[230:231]
	v_lshlrev_b32_e32 v230, 16, v34
	v_and_b32_e32 v231, 0xffff0000, v34
	v_pk_add_f32 v[210:211], v[210:211], v[230:231]
	v_lshlrev_b32_e32 v230, 16, v35
	v_and_b32_e32 v231, 0xffff0000, v35
	v_pk_add_f32 v[212:213], v[212:213], v[230:231]
	s_mov_b64 exec, s[72:73]
	s_waitcnt vmcnt(23)
; template <int NTOK, bool SMP>
; __device__ __forceinline__ void mixer_item(const Params& p, int it) {
;     ...
;         for (int q = 1; q < 16; ++q) if (q < w) { float f[8]; xpool(t0 - q, f);
; #pragma unroll
;             for (int i = 0; i < 8; ++i) s[i] += f[i]; }
; #pragma unroll 4
;         for (int t = 0; t < NTOK; ++t) {
;             const int tt = t0 + t; float x[8], y[8], f[8];
;             xpool(tt, x);
;             const float cnt = SMP ? (float)w : (float)min(w, tt + 1); const float ic = 1.0f / cnt;
; #pragma unroll
;             for (int i = 0; i < 8; ++i) { s[i] += x[i]; y[i] = s[i] * ic - x[i]; }
	v_lshlrev_b32_e32 v230, 16, v28
	v_and_b32_e32 v231, 0xffff0000, v28
	v_pk_add_f32 v[206:207], v[206:207], v[230:231]
	v_lshlrev_b32_e32 v230, 16, v29
	v_and_b32_e32 v231, 0xffff0000, v29
	v_pk_add_f32 v[208:209], v[208:209], v[230:231]
	v_lshlrev_b32_e32 v230, 16, v30
	v_and_b32_e32 v231, 0xffff0000, v30
	v_pk_add_f32 v[210:211], v[210:211], v[230:231]
	v_lshlrev_b32_e32 v230, 16, v31
	v_and_b32_e32 v231, 0xffff0000, v31
	v_pk_add_f32 v[212:213], v[212:213], v[230:231]
	s_waitcnt vmcnt(22)
	v_lshlrev_b32_e32 v230, 16, v24
	v_and_b32_e32 v231, 0xffff0000, v24
	v_pk_add_f32 v[206:207], v[206:207], v[230:231]
	v_lshlrev_b32_e32 v230, 16, v25
	v_and_b32_e32 v231, 0xffff0000, v25
	v_pk_add_f32 v[208:209], v[208:209], v[230:231]
	v_lshlrev_b32_e32 v230, 16, v26
	v_and_b32_e32 v231, 0xffff0000, v26
	v_pk_add_f32 v[210:211], v[210:211], v[230:231]
	v_lshlrev_b32_e32 v230, 16, v27
	v_and_b32_e32 v231, 0xffff0000, v27
	v_pk_add_f32 v[212:213], v[212:213], v[230:231]
	s_waitcnt vmcnt(21)
	v_lshlrev_b32_e32 v230, 16, v20
	v_and_b32_e32 v231, 0xffff0000, v20
	v_pk_add_f32 v[206:207], v[206:207], v[230:231]
	v_lshlrev_b32_e32 v230, 16, v21
	v_and_b32_e32 v231, 0xffff0000, v21
	v_pk_add_f32 v[208:209], v[208:209], v[230:231]
	v_lshlrev_b32_e32 v230, 16, v22
	v_and_b32_e32 v231, 0xffff0000, v22
	v_pk_add_f32 v[210:211], v[210:211], v[230:231]
	v_lshlrev_b32_e32 v230, 16, v23
	v_and_b32_e32 v231, 0xffff0000, v23
	v_pk_add_f32 v[212:213], v[212:213], v[230:231]
	s_waitcnt vmcnt(20)
	v_lshlrev_b32_e32 v230, 16, v16
	v_and_b32_e32 v231, 0xffff0000, v16
	v_pk_add_f32 v[206:207], v[206:207], v[230:231]
	v_lshlrev_b32_e32 v230, 16, v17
	v_and_b32_e32 v231, 0xffff0000, v17
	v_pk_add_f32 v[208:209], v[208:209], v[230:231]
	v_lshlrev_b32_e32 v230, 16, v18
	v_and_b32_e32 v231, 0xffff0000, v18
	v_pk_add_f32 v[210:211], v[210:211], v[230:231]
	v_lshlrev_b32_e32 v230, 16, v19
	v_and_b32_e32 v231, 0xffff0000, v19
	v_pk_add_f32 v[212:213], v[212:213], v[230:231]
	s_waitcnt vmcnt(19)
	v_lshlrev_b32_e32 v230, 16, v12
	v_and_b32_e32 v231, 0xffff0000, v12
	v_pk_add_f32 v[206:207], v[206:207], v[230:231]
	v_lshlrev_b32_e32 v230, 16, v13
	v_and_b32_e32 v231, 0xffff0000, v13
	v_pk_add_f32 v[208:209], v[208:209], v[230:231]
	v_lshlrev_b32_e32 v230, 16, v14
	v_and_b32_e32 v231, 0xffff0000, v14
	v_pk_add_f32 v[210:211], v[210:211], v[230:231]
	v_lshlrev_b32_e32 v230, 16, v15
	v_and_b32_e32 v231, 0xffff0000, v15
	v_pk_add_f32 v[212:213], v[212:213], v[230:231]
	s_waitcnt vmcnt(18)
	v_lshlrev_b32_e32 v230, 16, v8
	v_and_b32_e32 v231, 0xffff0000, v8
	v_pk_add_f32 v[206:207], v[206:207], v[230:231]
	v_lshlrev_b32_e32 v230, 16, v9
	v_and_b32_e32 v231, 0xffff0000, v9
	v_pk_add_f32 v[208:209], v[208:209], v[230:231]
	v_lshlrev_b32_e32 v230, 16, v10
	v_and_b32_e32 v231, 0xffff0000, v10
	v_pk_add_f32 v[210:211], v[210:211], v[230:231]
	v_lshlrev_b32_e32 v230, 16, v11
	v_and_b32_e32 v231, 0xffff0000, v11
	v_pk_add_f32 v[212:213], v[212:213], v[230:231]
	s_waitcnt vmcnt(17)
	v_lshlrev_b32_e32 v230, 16, v4
	v_and_b32_e32 v231, 0xffff0000, v4
	v_pk_add_f32 v[206:207], v[206:207], v[230:231]
	v_lshlrev_b32_e32 v230, 16, v5
	v_and_b32_e32 v231, 0xffff0000, v5
	v_pk_add_f32 v[208:209], v[208:209], v[230:231]
	v_lshlrev_b32_e32 v230, 16, v6
	v_and_b32_e32 v231, 0xffff0000, v6
	v_pk_add_f32 v[210:211], v[210:211], v[230:231]
	v_lshlrev_b32_e32 v230, 16, v7
	v_and_b32_e32 v231, 0xffff0000, v7
	v_pk_add_f32 v[212:213], v[212:213], v[230:231]
	s_waitcnt vmcnt(16)
	v_lshlrev_b32_e32 v230, 16, v0
	v_and_b32_e32 v231, 0xffff0000, v0
	v_pk_add_f32 v[206:207], v[206:207], v[230:231]
	v_lshlrev_b32_e32 v230, 16, v1
	v_and_b32_e32 v231, 0xffff0000, v1
	v_pk_add_f32 v[208:209], v[208:209], v[230:231]
	v_lshlrev_b32_e32 v230, 16, v2
	v_and_b32_e32 v231, 0xffff0000, v2
	v_pk_add_f32 v[210:211], v[210:211], v[230:231]
	v_lshlrev_b32_e32 v230, 16, v3
	v_and_b32_e32 v231, 0xffff0000, v3
	v_pk_add_f32 v[212:213], v[212:213], v[230:231]
	s_mov_b64 exec, s[76:77]
	s_waitcnt vmcnt(15)
	v_mov_b32_e32 v175, 0x3f800000
	v_cmp_lt_u32_e32 vcc, 1, v65
	s_and_b64 vcc, vcc, s[78:79]
	s_nop 1
	v_cndmask_b32_e32 v234, v72, v175, vcc
	v_lshlrev_b32_e32 v230, 16, v60
	v_and_b32_e32 v231, 0xffff0000, v60
	v_pk_add_f32 v[206:207], v[206:207], v[230:231]
	v_pk_fma_f32 v[232:233], v[234:235], v[206:207], v[230:231] op_sel_hi:[0,1,1] neg_lo:[0,0,1] neg_hi:[0,0,1]
	v_cvt_pk_bf16_f32 v214, v232, v233
	v_lshlrev_b32_e32 v230, 16, v61
	v_and_b32_e32 v231, 0xffff0000, v61
	v_pk_add_f32 v[208:209], v[208:209], v[230:231]
	v_pk_fma_f32 v[232:233], v[234:235], v[208:209], v[230:231] op_sel_hi:[0,1,1] neg_lo:[0,0,1] neg_hi:[0,0,1]
	v_cvt_pk_bf16_f32 v215, v232, v233
	v_lshlrev_b32_e32 v230, 16, v62
	v_and_b32_e32 v231, 0xffff0000, v62
	v_pk_add_f32 v[210:211], v[210:211], v[230:231]
	v_pk_fma_f32 v[232:233], v[234:235], v[210:211], v[230:231] op_sel_hi:[0,1,1] neg_lo:[0,0,1] neg_hi:[0,0,1]
	v_cvt_pk_bf16_f32 v216, v232, v233
	v_lshlrev_b32_e32 v230, 16, v63
	v_and_b32_e32 v231, 0xffff0000, v63
	v_pk_add_f32 v[212:213], v[212:213], v[230:231]
	v_pk_fma_f32 v[232:233], v[234:235], v[212:213], v[230:231] op_sel_hi:[0,1,1] neg_lo:[0,0,1] neg_hi:[0,0,1]
	v_cvt_pk_bf16_f32 v217, v232, v233
	global_store_dwordx4 v82, v[214:217], s[68:69]
	v_cndmask_b32_e64 v129, v32, v0, s[72:73]
	v_lshlrev_b32_e32 v158, 16, v129
	v_and_b32_e32 v159, 0xffff0000, v129
	v_pk_add_f32 v[206:207], v[206:207], v[158:159] neg_lo:[0,1] neg_hi:[0,1]
	v_cndmask_b32_e64 v129, v33, v1, s[72:73]
	v_lshlrev_b32_e32 v158, 16, v129
	v_and_b32_e32 v159, 0xffff0000, v129
	v_pk_add_f32 v[208:209], v[208:209], v[158:159] neg_lo:[0,1] neg_hi:[0,1]
	v_cndmask_b32_e64 v129, v34, v2, s[72:73]
	v_lshlrev_b32_e32 v158, 16, v129
	v_and_b32_e32 v159, 0xffff0000, v129
	v_pk_add_f32 v[210:211], v[210:211], v[158:159] neg_lo:[0,1] neg_hi:[0,1]
	v_cndmask_b32_e64 v129, v35, v3, s[72:73]
	v_lshlrev_b32_e32 v158, 16, v129
	v_and_b32_e32 v159, 0xffff0000, v129
	v_pk_add_f32 v[212:213], v[212:213], v[158:159] neg_lo:[0,1] neg_hi:[0,1]
	s_waitcnt vmcnt(15)
; __device__ __forceinline__ u32x4 pack8(const float* f) { u32x4 w; w.x = pk2(f[0], f[1]); w.y = pk2(f[2], f[3]); w.z = pk2(f[4], f[5]); w.w = pk2(f[6], f[7]); return w; }
; template <int NTOK, bool SMP>
; __device__ __forceinline__ void mixer_item(const Params& p, int it) {
;     ...
;         for (int t = 0; t < NTOK; ++t) {
;             const int tt = t0 + t; float x[8], y[8], f[8];
;             xpool(tt, x);
;             const float cnt = SMP ? (float)w : (float)min(w, tt + 1); const float ic = 1.0f / cnt;
; #pragma unroll
;             for (int i = 0; i < 8; ++i) { s[i] += x[i]; y[i] = s[i] * ic - x[i]; }
;             *(u32x4*)(yp + (size_t)(seqrow0 + tt) * 1024 + pc) = pack8(y);
;             xpool(tt - w + 1, f);
; #pragma unroll
;             for (int i = 0; i < 8; ++i) s[i] -= f[i];
;             if (SMP) { float* o = p.out + O_PS + ((size_t)sb * 15 + 11 + t) * 1024 + pc; *(f32x4*)o = (f32x4){x[0], x[1], x[2], x[3]}; *(f32x4*)(o + 4) = (f32x4){x[4], x[5], x[6], x[7]}; }
;             else if (tt >= 2033) { float* o = p.out + O_PP + ((size_t)b * 15 + (tt - 2033)) * 1024 + pc; *(f32x4*)o = (f32x4){x[0], x[1], x[2], x[3]}; *(f32x4*)(o + 4) = (f32x4){x[4], x[5], x[6], x[7]}; }
	v_mov_b32_e32 v175, 0x3f000000
	v_cmp_lt_u32_e32 vcc, 2, v65
	s_and_b64 vcc, vcc, s[78:79]
	s_nop 1
	v_cndmask_b32_e32 v234, v72, v175, vcc
	v_lshlrev_b32_e32 v230, 16, v130
	v_and_b32_e32 v231, 0xffff0000, v130
	v_pk_add_f32 v[206:207], v[206:207], v[230:231]
	v_pk_fma_f32 v[232:233], v[234:235], v[206:207], v[230:231] op_sel_hi:[0,1,1] neg_lo:[0,0,1] neg_hi:[0,0,1]
	v_cvt_pk_bf16_f32 v218, v232, v233
	v_lshlrev_b32_e32 v230, 16, v131
	v_and_b32_e32 v231, 0xffff0000, v131
	v_pk_add_f32 v[208:209], v[208:209], v[230:231]
	v_pk_fma_f32 v[232:233], v[234:235], v[208:209], v[230:231] op_sel_hi:[0,1,1] neg_lo:[0,0,1] neg_hi:[0,0,1]
	v_cvt_pk_bf16_f32 v219, v232, v233
	v_lshlrev_b32_e32 v230, 16, v132
	v_and_b32_e32 v231, 0xffff0000, v132
	v_pk_add_f32 v[210:211], v[210:211], v[230:231]
	v_pk_fma_f32 v[232:233], v[234:235], v[210:211], v[230:231] op_sel_hi:[0,1,1] neg_lo:[0,0,1] neg_hi:[0,0,1]
	v_cvt_pk_bf16_f32 v220, v232, v233
	v_lshlrev_b32_e32 v230, 16, v133
	v_and_b32_e32 v231, 0xffff0000, v133
	v_pk_add_f32 v[212:213], v[212:213], v[230:231]
	v_pk_fma_f32 v[232:233], v[234:235], v[212:213], v[230:231] op_sel_hi:[0,1,1] neg_lo:[0,0,1] neg_hi:[0,0,1]
	v_cvt_pk_bf16_f32 v221, v232, v233
	s_add_u32 s68, s68, 0x800
	s_addc_u32 s69, s69, 0
	global_store_dwordx4 v82, v[218:221], s[68:69]
	s_cmpk_lg_u32 s40, 0x7f0
	s_cbranch_scc1 .Lpl_w7_nopp1
	v_lshlrev_b32_e32 v222, 16, v130
	v_and_b32_e32 v223, 0xffff0000, v130
	v_lshlrev_b32_e32 v224, 16, v131
	v_and_b32_e32 v225, 0xffff0000, v131
	v_lshlrev_b32_e32 v226, 16, v132
	v_and_b32_e32 v227, 0xffff0000, v132
	v_lshlrev_b32_e32 v228, 16, v133
	v_and_b32_e32 v229, 0xffff0000, v133
	s_add_u32 s70, s70, 0x1000
	s_addc_u32 s71, s71, 0
	global_store_dwordx4 v185, v[222:225], s[70:71]
	global_store_dwordx4 v185, v[226:229], s[70:71] offset:16
.Lpl_w7_nopp1:
	v_cndmask_b32_e64 v129, v36, v4, s[72:73]
	v_lshlrev_b32_e32 v158, 16, v129
	v_and_b32_e32 v159, 0xffff0000, v129
	v_pk_add_f32 v[206:207], v[206:207], v[158:159] neg_lo:[0,1] neg_hi:[0,1]
	v_cndmask_b32_e64 v129, v37, v5, s[72:73]
	v_lshlrev_b32_e32 v158, 16, v129
	v_and_b32_e32 v159, 0xffff0000, v129
	v_pk_add_f32 v[208:209], v[208:209], v[158:159] neg_lo:[0,1] neg_hi:[0,1]
	v_cndmask_b32_e64 v129, v38, v6, s[72:73]
	v_lshlrev_b32_e32 v158, 16, v129
	v_and_b32_e32 v159, 0xffff0000, v129
	v_pk_add_f32 v[210:211], v[210:211], v[158:159] neg_lo:[0,1] neg_hi:[0,1]
	v_cndmask_b32_e64 v129, v39, v7, s[72:73]
	v_lshlrev_b32_e32 v158, 16, v129
	v_and_b32_e32 v159, 0xffff0000, v129
	v_pk_add_f32 v[212:213], v[212:213], v[158:159] neg_lo:[0,1] neg_hi:[0,1]
	s_waitcnt vmcnt(15)
	v_mov_b32_e32 v175, 0x3eaaaaab
	v_cmp_lt_u32_e32 vcc, 3, v65
	s_and_b64 vcc, vcc, s[78:79]
	s_nop 1
	v_cndmask_b32_e32 v234, v72, v175, vcc
	v_lshlrev_b32_e32 v230, 16, v134
	v_and_b32_e32 v231, 0xffff0000, v134
	v_pk_add_f32 v[206:207], v[206:207], v[230:231]
	v_pk_fma_f32 v[232:233], v[234:235], v[206:207], v[230:231] op_sel_hi:[0,1,1] neg_lo:[0,0,1] neg_hi:[0,0,1]
	v_cvt_pk_bf16_f32 v214, v232, v233
	v_lshlrev_b32_e32 v230, 16, v135
	v_and_b32_e32 v231, 0xffff0000, v135
	v_pk_add_f32 v[208:209], v[208:209], v[230:231]
	v_pk_fma_f32 v[232:233], v[234:235], v[208:209], v[230:231] op_sel_hi:[0,1,1] neg_lo:[0,0,1] neg_hi:[0,0,1]
	v_cvt_pk_bf16_f32 v215, v232, v233
	v_lshlrev_b32_e32 v230, 16, v136
	v_and_b32_e32 v231, 0xffff0000, v136
	v_pk_add_f32 v[210:211], v[210:211], v[230:231]
	v_pk_fma_f32 v[232:233], v[234:235], v[210:211], v[230:231] op_sel_hi:[0,1,1] neg_lo:[0,0,1] neg_hi:[0,0,1]
	v_cvt_pk_bf16_f32 v216, v232, v233
	v_lshlrev_b32_e32 v230, 16, v137
	v_and_b32_e32 v231, 0xffff0000, v137
	v_pk_add_f32 v[212:213], v[212:213], v[230:231]
	v_pk_fma_f32 v[232:233], v[234:235], v[212:213], v[230:231] op_sel_hi:[0,1,1] neg_lo:[0,0,1] neg_hi:[0,0,1]
	v_cvt_pk_bf16_f32 v217, v232, v233
	s_add_u32 s68, s68, 0x800
	s_addc_u32 s69, s69, 0
	global_store_dwordx4 v82, v[214:217], s[68:69]
	s_cmpk_lg_u32 s40, 0x7f0
	s_cbranch_scc1 .Lpl_w7_nopp2
	v_lshlrev_b32_e32 v222, 16, v134
	v_and_b32_e32 v223, 0xffff0000, v134
	v_lshlrev_b32_e32 v224, 16, v135
	v_and_b32_e32 v225, 0xffff0000, v135
	v_lshlrev_b32_e32 v226, 16, v136
	v_and_b32_e32 v227, 0xffff0000, v136
	v_lshlrev_b32_e32 v228, 16, v137
	v_and_b32_e32 v229, 0xffff0000, v137
	s_add_u32 s70, s70, 0x1000
	s_addc_u32 s71, s71, 0
	global_store_dwordx4 v185, v[222:225], s[70:71]
	global_store_dwordx4 v185, v[226:229], s[70:71] offset:16
; __device__ __forceinline__ u32x4 pack8(const float* f) { u32x4 w; w.x = pk2(f[0], f[1]); w.y = pk2(f[2], f[3]); w.z = pk2(f[4], f[5]); w.w = pk2(f[6], f[7]); return w; }
; template <int NTOK, bool SMP>
; __device__ __forceinline__ void mixer_item(const Params& p, int it) {
;     ...
;         for (int t = 0; t < NTOK; ++t) {
;             const int tt = t0 + t; float x[8], y[8], f[8];
;             xpool(tt, x);
;             const float cnt = SMP ? (float)w : (float)min(w, tt + 1); const float ic = 1.0f / cnt;
; #pragma unroll
;             for (int i = 0; i < 8; ++i) { s[i] += x[i]; y[i] = s[i] * ic - x[i]; }
;             *(u32x4*)(yp + (size_t)(seqrow0 + tt) * 1024 + pc) = pack8(y);
;             xpool(tt - w + 1, f);
; #pragma unroll
;             for (int i = 0; i < 8; ++i) s[i] -= f[i];
;             if (SMP) { float* o = p.out + O_PS + ((size_t)sb * 15 + 11 + t) * 1024 + pc; *(f32x4*)o = (f32x4){x[0], x[1], x[2], x[3]}; *(f32x4*)(o + 4) = (f32x4){x[4], x[5], x[6], x[7]}; }
;             else if (tt >= 2033) { float* o = p.out + O_PP + ((size_t)b * 15 + (tt - 2033)) * 1024 + pc; *(f32x4*)o = (f32x4){x[0], x[1], x[2], x[3]}; *(f32x4*)(o + 4) = (f32x4){x[4], x[5], x[6], x[7]}; }
.Lpl_w7_nopp2:
	v_cndmask_b32_e64 v129, v40, v8, s[72:73]
	v_lshlrev_b32_e32 v158, 16, v129
	v_and_b32_e32 v159, 0xffff0000, v129
	v_pk_add_f32 v[206:207], v[206:207], v[158:159] neg_lo:[0,1] neg_hi:[0,1]
	v_cndmask_b32_e64 v129, v41, v9, s[72:73]
	v_lshlrev_b32_e32 v158, 16, v129
	v_and_b32_e32 v159, 0xffff0000, v129
	v_pk_add_f32 v[208:209], v[208:209], v[158:159] neg_lo:[0,1] neg_hi:[0,1]
	v_cndmask_b32_e64 v129, v42, v10, s[72:73]
	v_lshlrev_b32_e32 v158, 16, v129
	v_and_b32_e32 v159, 0xffff0000, v129
	v_pk_add_f32 v[210:211], v[210:211], v[158:159] neg_lo:[0,1] neg_hi:[0,1]
	v_cndmask_b32_e64 v129, v43, v11, s[72:73]
	v_lshlrev_b32_e32 v158, 16, v129
	v_and_b32_e32 v159, 0xffff0000, v129
	v_pk_add_f32 v[212:213], v[212:213], v[158:159] neg_lo:[0,1] neg_hi:[0,1]
	s_waitcnt vmcnt(15)
	v_mov_b32_e32 v175, 0x3e800000
	v_cmp_lt_u32_e32 vcc, 4, v65
	s_and_b64 vcc, vcc, s[78:79]
	s_nop 1
	v_cndmask_b32_e32 v234, v72, v175, vcc
	v_lshlrev_b32_e32 v230, 16, v138
	v_and_b32_e32 v231, 0xffff0000, v138
	v_pk_add_f32 v[206:207], v[206:207], v[230:231]
	v_pk_fma_f32 v[232:233], v[234:235], v[206:207], v[230:231] op_sel_hi:[0,1,1] neg_lo:[0,0,1] neg_hi:[0,0,1]
	v_cvt_pk_bf16_f32 v218, v232, v233
	v_lshlrev_b32_e32 v230, 16, v139
	v_and_b32_e32 v231, 0xffff0000, v139
	v_pk_add_f32 v[208:209], v[208:209], v[230:231]
	v_pk_fma_f32 v[232:233], v[234:235], v[208:209], v[230:231] op_sel_hi:[0,1,1] neg_lo:[0,0,1] neg_hi:[0,0,1]
	v_cvt_pk_bf16_f32 v219, v232, v233
	v_lshlrev_b32_e32 v230, 16, v140
	v_and_b32_e32 v231, 0xffff0000, v140
	v_pk_add_f32 v[210:211], v[210:211], v[230:231]
	v_pk_fma_f32 v[232:233], v[234:235], v[210:211], v[230:231] op_sel_hi:[0,1,1] neg_lo:[0,0,1] neg_hi:[0,0,1]
	v_cvt_pk_bf16_f32 v220, v232, v233
	v_lshlrev_b32_e32 v230, 16, v141
	v_and_b32_e32 v231, 0xffff0000, v141
	v_pk_add_f32 v[212:213], v[212:213], v[230:231]
	v_pk_fma_f32 v[232:233], v[234:235], v[212:213], v[230:231] op_sel_hi:[0,1,1] neg_lo:[0,0,1] neg_hi:[0,0,1]
	v_cvt_pk_bf16_f32 v221, v232, v233
	s_add_u32 s68, s68, 0x800
	s_addc_u32 s69, s69, 0
	global_store_dwordx4 v82, v[218:221], s[68:69]
	s_cmpk_lg_u32 s40, 0x7f0
	s_cbranch_scc1 .Lpl_w7_nopp3
	v_lshlrev_b32_e32 v222, 16, v138
	v_and_b32_e32 v223, 0xffff0000, v138
	v_lshlrev_b32_e32 v224, 16, v139
	v_and_b32_e32 v225, 0xffff0000, v139
	v_lshlrev_b32_e32 v226, 16, v140
	v_and_b32_e32 v227, 0xffff0000, v140
	v_lshlrev_b32_e32 v228, 16, v141
	v_and_b32_e32 v229, 0xffff0000, v141
	s_add_u32 s70, s70, 0x1000
	s_addc_u32 s71, s71, 0
	global_store_dwordx4 v185, v[222:225], s[70:71]
	global_store_dwordx4 v185, v[226:229], s[70:71] offset:16
.Lpl_w7_nopp3:
	v_cndmask_b32_e64 v129, v44, v12, s[72:73]
	v_lshlrev_b32_e32 v158, 16, v129
	v_and_b32_e32 v159, 0xffff0000, v129
	v_pk_add_f32 v[206:207], v[206:207], v[158:159] neg_lo:[0,1] neg_hi:[0,1]
	v_cndmask_b32_e64 v129, v45, v13, s[72:73]
	v_lshlrev_b32_e32 v158, 16, v129
	v_and_b32_e32 v159, 0xffff0000, v129
	v_pk_add_f32 v[208:209], v[208:209], v[158:159] neg_lo:[0,1] neg_hi:[0,1]
	v_cndmask_b32_e64 v129, v46, v14, s[72:73]
	v_lshlrev_b32_e32 v158, 16, v129
	v_and_b32_e32 v159, 0xffff0000, v129
	v_pk_add_f32 v[210:211], v[210:211], v[158:159] neg_lo:[0,1] neg_hi:[0,1]
	v_cndmask_b32_e64 v129, v47, v15, s[72:73]
	v_lshlrev_b32_e32 v158, 16, v129
	v_and_b32_e32 v159, 0xffff0000, v129
	v_pk_add_f32 v[212:213], v[212:213], v[158:159] neg_lo:[0,1] neg_hi:[0,1]
	s_waitcnt vmcnt(15)
	v_mov_b32_e32 v175, 0x3e4ccccd
	v_cmp_lt_u32_e32 vcc, 5, v65
	s_and_b64 vcc, vcc, s[78:79]
	s_nop 1
	v_cndmask_b32_e32 v234, v72, v175, vcc
	v_lshlrev_b32_e32 v230, 16, v142
	v_and_b32_e32 v231, 0xffff0000, v142
	v_pk_add_f32 v[206:207], v[206:207], v[230:231]
	v_pk_fma_f32 v[232:233], v[234:235], v[206:207], v[230:231] op_sel_hi:[0,1,1] neg_lo:[0,0,1] neg_hi:[0,0,1]
	v_cvt_pk_bf16_f32 v214, v232, v233
	v_lshlrev_b32_e32 v230, 16, v143
	v_and_b32_e32 v231, 0xffff0000, v143
	v_pk_add_f32 v[208:209], v[208:209], v[230:231]
	v_pk_fma_f32 v[232:233], v[234:235], v[208:209], v[230:231] op_sel_hi:[0,1,1] neg_lo:[0,0,1] neg_hi:[0,0,1]
	v_cvt_pk_bf16_f32 v215, v232, v233
	v_lshlrev_b32_e32 v230, 16, v144
	v_and_b32_e32 v231, 0xffff0000, v144
	v_pk_add_f32 v[210:211], v[210:211], v[230:231]
	v_pk_fma_f32 v[232:233], v[234:235], v[210:211], v[230:231] op_sel_hi:[0,1,1] neg_lo:[0,0,1] neg_hi:[0,0,1]
	v_cvt_pk_bf16_f32 v216, v232, v233
	v_lshlrev_b32_e32 v230, 16, v145
	v_and_b32_e32 v231, 0xffff0000, v145
	v_pk_add_f32 v[212:213], v[212:213], v[230:231]
	v_pk_fma_f32 v[232:233], v[234:235], v[212:213], v[230:231] op_sel_hi:[0,1,1] neg_lo:[0,0,1] neg_hi:[0,0,1]
	v_cvt_pk_bf16_f32 v217, v232, v233
	s_add_u32 s68, s68, 0x800
	s_addc_u32 s69, s69, 0
	global_store_dwordx4 v82, v[214:217], s[68:69]
	s_cmpk_lg_u32 s40, 0x7f0
	s_cbranch_scc1 .Lpl_w7_nopp4
	v_lshlrev_b32_e32 v222, 16, v142
	v_and_b32_e32 v223, 0xffff0000, v142
	v_lshlrev_b32_e32 v224, 16, v143
	v_and_b32_e32 v225, 0xffff0000, v143
	v_lshlrev_b32_e32 v226, 16, v144
	v_and_b32_e32 v227, 0xffff0000, v144
	v_lshlrev_b32_e32 v228, 16, v145
	v_and_b32_e32 v229, 0xffff0000, v145
	s_add_u32 s70, s70, 0x1000
	s_addc_u32 s71, s71, 0
	global_store_dwordx4 v185, v[222:225], s[70:71]
	global_store_dwordx4 v185, v[226:229], s[70:71] offset:16
; __device__ __forceinline__ u32x4 pack8(const float* f) { u32x4 w; w.x = pk2(f[0], f[1]); w.y = pk2(f[2], f[3]); w.z = pk2(f[4], f[5]); w.w = pk2(f[6], f[7]); return w; }
; template <int NTOK, bool SMP>
; __device__ __forceinline__ void mixer_item(const Params& p, int it) {
;     ...
;         for (int t = 0; t < NTOK; ++t) {
;             const int tt = t0 + t; float x[8], y[8], f[8];
;             xpool(tt, x);
;             const float cnt = SMP ? (float)w : (float)min(w, tt + 1); const float ic = 1.0f / cnt;
; #pragma unroll
;             for (int i = 0; i < 8; ++i) { s[i] += x[i]; y[i] = s[i] * ic - x[i]; }
;             *(u32x4*)(yp + (size_t)(seqrow0 + tt) * 1024 + pc) = pack8(y);
;             xpool(tt - w + 1, f);
; #pragma unroll
;             for (int i = 0; i < 8; ++i) s[i] -= f[i];
;             if (SMP) { float* o = p.out + O_PS + ((size_t)sb * 15 + 11 + t) * 1024 + pc; *(f32x4*)o = (f32x4){x[0], x[1], x[2], x[3]}; *(f32x4*)(o + 4) = (f32x4){x[4], x[5], x[6], x[7]}; }
;             else if (tt >= 2033) { float* o = p.out + O_PP + ((size_t)b * 15 + (tt - 2033)) * 1024 + pc; *(f32x4*)o = (f32x4){x[0], x[1], x[2], x[3]}; *(f32x4*)(o + 4) = (f32x4){x[4], x[5], x[6], x[7]}; }
.Lpl_w7_nopp4:
	v_cndmask_b32_e64 v129, v48, v16, s[72:73]
	v_lshlrev_b32_e32 v158, 16, v129
	v_and_b32_e32 v159, 0xffff0000, v129
	v_pk_add_f32 v[206:207], v[206:207], v[158:159] neg_lo:[0,1] neg_hi:[0,1]
	v_cndmask_b32_e64 v129, v49, v17, s[72:73]
	v_lshlrev_b32_e32 v158, 16, v129
	v_and_b32_e32 v159, 0xffff0000, v129
	v_pk_add_f32 v[208:209], v[208:209], v[158:159] neg_lo:[0,1] neg_hi:[0,1]
	v_cndmask_b32_e64 v129, v50, v18, s[72:73]
	v_lshlrev_b32_e32 v158, 16, v129
	v_and_b32_e32 v159, 0xffff0000, v129
	v_pk_add_f32 v[210:211], v[210:211], v[158:159] neg_lo:[0,1] neg_hi:[0,1]
	v_cndmask_b32_e64 v129, v51, v19, s[72:73]
	v_lshlrev_b32_e32 v158, 16, v129
	v_and_b32_e32 v159, 0xffff0000, v129
	v_pk_add_f32 v[212:213], v[212:213], v[158:159] neg_lo:[0,1] neg_hi:[0,1]
	s_waitcnt vmcnt(15)
	v_mov_b32_e32 v175, 0x3e2aaaab
	v_cmp_lt_u32_e32 vcc, 6, v65
	s_and_b64 vcc, vcc, s[78:79]
	s_nop 1
	v_cndmask_b32_e32 v234, v72, v175, vcc
	v_lshlrev_b32_e32 v230, 16, v146
	v_and_b32_e32 v231, 0xffff0000, v146
	v_pk_add_f32 v[206:207], v[206:207], v[230:231]
	v_pk_fma_f32 v[232:233], v[234:235], v[206:207], v[230:231] op_sel_hi:[0,1,1] neg_lo:[0,0,1] neg_hi:[0,0,1]
	v_cvt_pk_bf16_f32 v218, v232, v233
	v_lshlrev_b32_e32 v230, 16, v147
	v_and_b32_e32 v231, 0xffff0000, v147
	v_pk_add_f32 v[208:209], v[208:209], v[230:231]
	v_pk_fma_f32 v[232:233], v[234:235], v[208:209], v[230:231] op_sel_hi:[0,1,1] neg_lo:[0,0,1] neg_hi:[0,0,1]
	v_cvt_pk_bf16_f32 v219, v232, v233
	v_lshlrev_b32_e32 v230, 16, v148
	v_and_b32_e32 v231, 0xffff0000, v148
	v_pk_add_f32 v[210:211], v[210:211], v[230:231]
	v_pk_fma_f32 v[232:233], v[234:235], v[210:211], v[230:231] op_sel_hi:[0,1,1] neg_lo:[0,0,1] neg_hi:[0,0,1]
	v_cvt_pk_bf16_f32 v220, v232, v233
	v_lshlrev_b32_e32 v230, 16, v149
	v_and_b32_e32 v231, 0xffff0000, v149
	v_pk_add_f32 v[212:213], v[212:213], v[230:231]
	v_pk_fma_f32 v[232:233], v[234:235], v[212:213], v[230:231] op_sel_hi:[0,1,1] neg_lo:[0,0,1] neg_hi:[0,0,1]
	v_cvt_pk_bf16_f32 v221, v232, v233
	s_add_u32 s68, s68, 0x800
	s_addc_u32 s69, s69, 0
	global_store_dwordx4 v82, v[218:221], s[68:69]
	s_cmpk_lg_u32 s40, 0x7f0
	s_cbranch_scc1 .Lpl_w7_nopp5
	v_lshlrev_b32_e32 v222, 16, v146
	v_and_b32_e32 v223, 0xffff0000, v146
	v_lshlrev_b32_e32 v224, 16, v147
	v_and_b32_e32 v225, 0xffff0000, v147
	v_lshlrev_b32_e32 v226, 16, v148
	v_and_b32_e32 v227, 0xffff0000, v148
	v_lshlrev_b32_e32 v228, 16, v149
	v_and_b32_e32 v229, 0xffff0000, v149
	s_add_u32 s70, s70, 0x1000
	s_addc_u32 s71, s71, 0
	global_store_dwordx4 v185, v[222:225], s[70:71]
	global_store_dwordx4 v185, v[226:229], s[70:71] offset:16
.Lpl_w7_nopp5:
	v_cndmask_b32_e64 v129, v52, v20, s[72:73]
	v_lshlrev_b32_e32 v158, 16, v129
	v_and_b32_e32 v159, 0xffff0000, v129
	v_pk_add_f32 v[206:207], v[206:207], v[158:159] neg_lo:[0,1] neg_hi:[0,1]
	v_cndmask_b32_e64 v129, v53, v21, s[72:73]
	v_lshlrev_b32_e32 v158, 16, v129
	v_and_b32_e32 v159, 0xffff0000, v129
	v_pk_add_f32 v[208:209], v[208:209], v[158:159] neg_lo:[0,1] neg_hi:[0,1]
	v_cndmask_b32_e64 v129, v54, v22, s[72:73]
	v_lshlrev_b32_e32 v158, 16, v129
	v_and_b32_e32 v159, 0xffff0000, v129
	v_pk_add_f32 v[210:211], v[210:211], v[158:159] neg_lo:[0,1] neg_hi:[0,1]
	v_cndmask_b32_e64 v129, v55, v23, s[72:73]
	v_lshlrev_b32_e32 v158, 16, v129
	v_and_b32_e32 v159, 0xffff0000, v129
	v_pk_add_f32 v[212:213], v[212:213], v[158:159] neg_lo:[0,1] neg_hi:[0,1]
	s_waitcnt vmcnt(15)
	v_mov_b32_e32 v175, 0x3e124925
	v_cmp_lt_u32_e32 vcc, 7, v65
	s_and_b64 vcc, vcc, s[78:79]
	s_nop 1
	v_cndmask_b32_e32 v234, v72, v175, vcc
	v_lshlrev_b32_e32 v230, 16, v150
	v_and_b32_e32 v231, 0xffff0000, v150
	v_pk_add_f32 v[206:207], v[206:207], v[230:231]
	v_pk_fma_f32 v[232:233], v[234:235], v[206:207], v[230:231] op_sel_hi:[0,1,1] neg_lo:[0,0,1] neg_hi:[0,0,1]
	v_cvt_pk_bf16_f32 v214, v232, v233
	v_lshlrev_b32_e32 v230, 16, v151
	v_and_b32_e32 v231, 0xffff0000, v151
	v_pk_add_f32 v[208:209], v[208:209], v[230:231]
	v_pk_fma_f32 v[232:233], v[234:235], v[208:209], v[230:231] op_sel_hi:[0,1,1] neg_lo:[0,0,1] neg_hi:[0,0,1]
	v_cvt_pk_bf16_f32 v215, v232, v233
	v_lshlrev_b32_e32 v230, 16, v152
	v_and_b32_e32 v231, 0xffff0000, v152
	v_pk_add_f32 v[210:211], v[210:211], v[230:231]
	v_pk_fma_f32 v[232:233], v[234:235], v[210:211], v[230:231] op_sel_hi:[0,1,1] neg_lo:[0,0,1] neg_hi:[0,0,1]
	v_cvt_pk_bf16_f32 v216, v232, v233
	v_lshlrev_b32_e32 v230, 16, v153
	v_and_b32_e32 v231, 0xffff0000, v153
	v_pk_add_f32 v[212:213], v[212:213], v[230:231]
	v_pk_fma_f32 v[232:233], v[234:235], v[212:213], v[230:231] op_sel_hi:[0,1,1] neg_lo:[0,0,1] neg_hi:[0,0,1]
	v_cvt_pk_bf16_f32 v217, v232, v233
	s_add_u32 s68, s68, 0x800
	s_addc_u32 s69, s69, 0
	global_store_dwordx4 v82, v[214:217], s[68:69]
	s_cmpk_lg_u32 s40, 0x7f0
	s_cbranch_scc1 .Lpl_w7_nopp6
	v_lshlrev_b32_e32 v222, 16, v150
	v_and_b32_e32 v223, 0xffff0000, v150
	v_lshlrev_b32_e32 v224, 16, v151
	v_and_b32_e32 v225, 0xffff0000, v151
	v_lshlrev_b32_e32 v226, 16, v152
	v_and_b32_e32 v227, 0xffff0000, v152
	v_lshlrev_b32_e32 v228, 16, v153
	v_and_b32_e32 v229, 0xffff0000, v153
	s_add_u32 s70, s70, 0x1000
	s_addc_u32 s71, s71, 0
	global_store_dwordx4 v185, v[222:225], s[70:71]
	global_store_dwordx4 v185, v[226:229], s[70:71] offset:16
; __device__ __forceinline__ u32x4 pack8(const float* f) { u32x4 w; w.x = pk2(f[0], f[1]); w.y = pk2(f[2], f[3]); w.z = pk2(f[4], f[5]); w.w = pk2(f[6], f[7]); return w; }
; template <int NTOK, bool SMP>
; __device__ __forceinline__ void mixer_item(const Params& p, int it) {
;     ...
;         for (int t = 0; t < NTOK; ++t) {
;             const int tt = t0 + t; float x[8], y[8], f[8];
;             xpool(tt, x);
;             const float cnt = SMP ? (float)w : (float)min(w, tt + 1); const float ic = 1.0f / cnt;
; #pragma unroll
;             for (int i = 0; i < 8; ++i) { s[i] += x[i]; y[i] = s[i] * ic - x[i]; }
;             *(u32x4*)(yp + (size_t)(seqrow0 + tt) * 1024 + pc) = pack8(y);
;             xpool(tt - w + 1, f);
; #pragma unroll
;             for (int i = 0; i < 8; ++i) s[i] -= f[i];
;             if (SMP) { float* o = p.out + O_PS + ((size_t)sb * 15 + 11 + t) * 1024 + pc; *(f32x4*)o = (f32x4){x[0], x[1], x[2], x[3]}; *(f32x4*)(o + 4) = (f32x4){x[4], x[5], x[6], x[7]}; }
;             else if (tt >= 2033) { float* o = p.out + O_PP + ((size_t)b * 15 + (tt - 2033)) * 1024 + pc; *(f32x4*)o = (f32x4){x[0], x[1], x[2], x[3]}; *(f32x4*)(o + 4) = (f32x4){x[4], x[5], x[6], x[7]}; }
.Lpl_w7_nopp6:
	v_cndmask_b32_e64 v129, v56, v24, s[72:73]
	v_lshlrev_b32_e32 v158, 16, v129
	v_and_b32_e32 v159, 0xffff0000, v129
	v_pk_add_f32 v[206:207], v[206:207], v[158:159] neg_lo:[0,1] neg_hi:[0,1]
	v_cndmask_b32_e64 v129, v57, v25, s[72:73]
	v_lshlrev_b32_e32 v158, 16, v129
	v_and_b32_e32 v159, 0xffff0000, v129
	v_pk_add_f32 v[208:209], v[208:209], v[158:159] neg_lo:[0,1] neg_hi:[0,1]
	v_cndmask_b32_e64 v129, v58, v26, s[72:73]
	v_lshlrev_b32_e32 v158, 16, v129
	v_and_b32_e32 v159, 0xffff0000, v129
	v_pk_add_f32 v[210:211], v[210:211], v[158:159] neg_lo:[0,1] neg_hi:[0,1]
	v_cndmask_b32_e64 v129, v59, v27, s[72:73]
	v_lshlrev_b32_e32 v158, 16, v129
	v_and_b32_e32 v159, 0xffff0000, v129
	v_pk_add_f32 v[212:213], v[212:213], v[158:159] neg_lo:[0,1] neg_hi:[0,1]
	s_waitcnt vmcnt(15)
	v_mov_b32_e32 v175, 0x3e000000
	v_cmp_lt_u32_e32 vcc, 8, v65
	s_and_b64 vcc, vcc, s[78:79]
	s_nop 1
	v_cndmask_b32_e32 v234, v72, v175, vcc
	v_lshlrev_b32_e32 v230, 16, v154
	v_and_b32_e32 v231, 0xffff0000, v154
	v_pk_add_f32 v[206:207], v[206:207], v[230:231]
	v_pk_fma_f32 v[232:233], v[234:235], v[206:207], v[230:231] op_sel_hi:[0,1,1] neg_lo:[0,0,1] neg_hi:[0,0,1]
	v_cvt_pk_bf16_f32 v218, v232, v233
	v_lshlrev_b32_e32 v230, 16, v155
	v_and_b32_e32 v231, 0xffff0000, v155
	v_pk_add_f32 v[208:209], v[208:209], v[230:231]
	v_pk_fma_f32 v[232:233], v[234:235], v[208:209], v[230:231] op_sel_hi:[0,1,1] neg_lo:[0,0,1] neg_hi:[0,0,1]
	v_cvt_pk_bf16_f32 v219, v232, v233
	v_lshlrev_b32_e32 v230, 16, v156
	v_and_b32_e32 v231, 0xffff0000, v156
	v_pk_add_f32 v[210:211], v[210:211], v[230:231]
	v_pk_fma_f32 v[232:233], v[234:235], v[210:211], v[230:231] op_sel_hi:[0,1,1] neg_lo:[0,0,1] neg_hi:[0,0,1]
	v_cvt_pk_bf16_f32 v220, v232, v233
	v_lshlrev_b32_e32 v230, 16, v157
	v_and_b32_e32 v231, 0xffff0000, v157
	v_pk_add_f32 v[212:213], v[212:213], v[230:231]
	v_pk_fma_f32 v[232:233], v[234:235], v[212:213], v[230:231] op_sel_hi:[0,1,1] neg_lo:[0,0,1] neg_hi:[0,0,1]
	v_cvt_pk_bf16_f32 v221, v232, v233
	s_add_u32 s68, s68, 0x800
	s_addc_u32 s69, s69, 0
	global_store_dwordx4 v82, v[218:221], s[68:69]
	s_cmpk_lg_u32 s40, 0x7f0
	s_cbranch_scc1 .Lpl_w7_nopp7
	v_lshlrev_b32_e32 v222, 16, v154
	v_and_b32_e32 v223, 0xffff0000, v154
	v_lshlrev_b32_e32 v224, 16, v155
	v_and_b32_e32 v225, 0xffff0000, v155
	v_lshlrev_b32_e32 v226, 16, v156
	v_and_b32_e32 v227, 0xffff0000, v156
	v_lshlrev_b32_e32 v228, 16, v157
	v_and_b32_e32 v229, 0xffff0000, v157
	s_add_u32 s70, s70, 0x1000
	s_addc_u32 s71, s71, 0
	global_store_dwordx4 v185, v[222:225], s[70:71]
	global_store_dwordx4 v185, v[226:229], s[70:71] offset:16
.Lpl_w7_nopp7:
	v_cndmask_b32_e64 v129, v60, v28, s[72:73]
	v_lshlrev_b32_e32 v158, 16, v129
	v_and_b32_e32 v159, 0xffff0000, v129
	v_pk_add_f32 v[206:207], v[206:207], v[158:159] neg_lo:[0,1] neg_hi:[0,1]
	v_cndmask_b32_e64 v129, v61, v29, s[72:73]
	v_lshlrev_b32_e32 v158, 16, v129
	v_and_b32_e32 v159, 0xffff0000, v129
	v_pk_add_f32 v[208:209], v[208:209], v[158:159] neg_lo:[0,1] neg_hi:[0,1]
	v_cndmask_b32_e64 v129, v62, v30, s[72:73]
	v_lshlrev_b32_e32 v158, 16, v129
	v_and_b32_e32 v159, 0xffff0000, v129
	v_pk_add_f32 v[210:211], v[210:211], v[158:159] neg_lo:[0,1] neg_hi:[0,1]
	v_cndmask_b32_e64 v129, v63, v31, s[72:73]
	v_lshlrev_b32_e32 v158, 16, v129
	v_and_b32_e32 v159, 0xffff0000, v129
	v_pk_add_f32 v[212:213], v[212:213], v[158:159] neg_lo:[0,1] neg_hi:[0,1]
	s_waitcnt vmcnt(15)
	v_mov_b32_e32 v175, 0x3de38e39
	v_cmp_lt_u32_e32 vcc, 9, v65
	s_and_b64 vcc, vcc, s[78:79]
	s_nop 1
	v_cndmask_b32_e32 v234, v72, v175, vcc
	v_lshlrev_b32_e32 v230, 16, v162
	v_and_b32_e32 v231, 0xffff0000, v162
	v_pk_add_f32 v[206:207], v[206:207], v[230:231]
	v_pk_fma_f32 v[232:233], v[234:235], v[206:207], v[230:231] op_sel_hi:[0,1,1] neg_lo:[0,0,1] neg_hi:[0,0,1]
	v_cvt_pk_bf16_f32 v214, v232, v233
	v_lshlrev_b32_e32 v230, 16, v163
	v_and_b32_e32 v231, 0xffff0000, v163
	v_pk_add_f32 v[208:209], v[208:209], v[230:231]
	v_pk_fma_f32 v[232:233], v[234:235], v[208:209], v[230:231] op_sel_hi:[0,1,1] neg_lo:[0,0,1] neg_hi:[0,0,1]
	v_cvt_pk_bf16_f32 v215, v232, v233
	v_lshlrev_b32_e32 v230, 16, v164
	v_and_b32_e32 v231, 0xffff0000, v164
	v_pk_add_f32 v[210:211], v[210:211], v[230:231]
	v_pk_fma_f32 v[232:233], v[234:235], v[210:211], v[230:231] op_sel_hi:[0,1,1] neg_lo:[0,0,1] neg_hi:[0,0,1]
	v_cvt_pk_bf16_f32 v216, v232, v233
	v_lshlrev_b32_e32 v230, 16, v165
	v_and_b32_e32 v231, 0xffff0000, v165
	v_pk_add_f32 v[212:213], v[212:213], v[230:231]
	v_pk_fma_f32 v[232:233], v[234:235], v[212:213], v[230:231] op_sel_hi:[0,1,1] neg_lo:[0,0,1] neg_hi:[0,0,1]
	v_cvt_pk_bf16_f32 v217, v232, v233
	s_add_u32 s68, s68, 0x800
	s_addc_u32 s69, s69, 0
	global_store_dwordx4 v82, v[214:217], s[68:69]
	s_cmpk_lg_u32 s40, 0x7f0
	s_cbranch_scc1 .Lpl_w7_nopp8
	v_lshlrev_b32_e32 v222, 16, v162
	v_and_b32_e32 v223, 0xffff0000, v162
	v_lshlrev_b32_e32 v224, 16, v163
	v_and_b32_e32 v225, 0xffff0000, v163
	v_lshlrev_b32_e32 v226, 16, v164
	v_and_b32_e32 v227, 0xffff0000, v164
	v_lshlrev_b32_e32 v228, 16, v165
	v_and_b32_e32 v229, 0xffff0000, v165
	s_add_u32 s70, s70, 0x1000
	s_addc_u32 s71, s71, 0
	global_store_dwordx4 v185, v[222:225], s[70:71]
	global_store_dwordx4 v185, v[226:229], s[70:71] offset:16
; __device__ __forceinline__ u32x4 pack8(const float* f) { u32x4 w; w.x = pk2(f[0], f[1]); w.y = pk2(f[2], f[3]); w.z = pk2(f[4], f[5]); w.w = pk2(f[6], f[7]); return w; }
; template <int NTOK, bool SMP>
; __device__ __forceinline__ void mixer_item(const Params& p, int it) {
;     ...
;         for (int t = 0; t < NTOK; ++t) {
;             const int tt = t0 + t; float x[8], y[8], f[8];
;             xpool(tt, x);
;             const float cnt = SMP ? (float)w : (float)min(w, tt + 1); const float ic = 1.0f / cnt;
; #pragma unroll
;             for (int i = 0; i < 8; ++i) { s[i] += x[i]; y[i] = s[i] * ic - x[i]; }
;             *(u32x4*)(yp + (size_t)(seqrow0 + tt) * 1024 + pc) = pack8(y);
;             xpool(tt - w + 1, f);
; #pragma unroll
;             for (int i = 0; i < 8; ++i) s[i] -= f[i];
;             if (SMP) { float* o = p.out + O_PS + ((size_t)sb * 15 + 11 + t) * 1024 + pc; *(f32x4*)o = (f32x4){x[0], x[1], x[2], x[3]}; *(f32x4*)(o + 4) = (f32x4){x[4], x[5], x[6], x[7]}; }
;             else if (tt >= 2033) { float* o = p.out + O_PP + ((size_t)b * 15 + (tt - 2033)) * 1024 + pc; *(f32x4*)o = (f32x4){x[0], x[1], x[2], x[3]}; *(f32x4*)(o + 4) = (f32x4){x[4], x[5], x[6], x[7]}; }
.Lpl_w7_nopp8:
	v_cndmask_b32_e64 v129, v130, v32, s[72:73]
	v_lshlrev_b32_e32 v158, 16, v129
	v_and_b32_e32 v159, 0xffff0000, v129
	v_pk_add_f32 v[206:207], v[206:207], v[158:159] neg_lo:[0,1] neg_hi:[0,1]
	v_cndmask_b32_e64 v129, v131, v33, s[72:73]
	v_lshlrev_b32_e32 v158, 16, v129
	v_and_b32_e32 v159, 0xffff0000, v129
	v_pk_add_f32 v[208:209], v[208:209], v[158:159] neg_lo:[0,1] neg_hi:[0,1]
	v_cndmask_b32_e64 v129, v132, v34, s[72:73]
	v_lshlrev_b32_e32 v158, 16, v129
	v_and_b32_e32 v159, 0xffff0000, v129
	v_pk_add_f32 v[210:211], v[210:211], v[158:159] neg_lo:[0,1] neg_hi:[0,1]
	v_cndmask_b32_e64 v129, v133, v35, s[72:73]
	v_lshlrev_b32_e32 v158, 16, v129
	v_and_b32_e32 v159, 0xffff0000, v129
	v_pk_add_f32 v[212:213], v[212:213], v[158:159] neg_lo:[0,1] neg_hi:[0,1]
	s_waitcnt vmcnt(15)
	v_mov_b32_e32 v175, 0x3dcccccd
	v_cmp_lt_u32_e32 vcc, 10, v65
	s_and_b64 vcc, vcc, s[78:79]
	s_nop 1
	v_cndmask_b32_e32 v234, v72, v175, vcc
	v_lshlrev_b32_e32 v230, 16, v176
	v_and_b32_e32 v231, 0xffff0000, v176
	v_pk_add_f32 v[206:207], v[206:207], v[230:231]
	v_pk_fma_f32 v[232:233], v[234:235], v[206:207], v[230:231] op_sel_hi:[0,1,1] neg_lo:[0,0,1] neg_hi:[0,0,1]
	v_cvt_pk_bf16_f32 v218, v232, v233
	v_lshlrev_b32_e32 v230, 16, v177
	v_and_b32_e32 v231, 0xffff0000, v177
	v_pk_add_f32 v[208:209], v[208:209], v[230:231]
	v_pk_fma_f32 v[232:233], v[234:235], v[208:209], v[230:231] op_sel_hi:[0,1,1] neg_lo:[0,0,1] neg_hi:[0,0,1]
	v_cvt_pk_bf16_f32 v219, v232, v233
	v_lshlrev_b32_e32 v230, 16, v178
	v_and_b32_e32 v231, 0xffff0000, v178
	v_pk_add_f32 v[210:211], v[210:211], v[230:231]
	v_pk_fma_f32 v[232:233], v[234:235], v[210:211], v[230:231] op_sel_hi:[0,1,1] neg_lo:[0,0,1] neg_hi:[0,0,1]
	v_cvt_pk_bf16_f32 v220, v232, v233
	v_lshlrev_b32_e32 v230, 16, v179
	v_and_b32_e32 v231, 0xffff0000, v179
	v_pk_add_f32 v[212:213], v[212:213], v[230:231]
	v_pk_fma_f32 v[232:233], v[234:235], v[212:213], v[230:231] op_sel_hi:[0,1,1] neg_lo:[0,0,1] neg_hi:[0,0,1]
	v_cvt_pk_bf16_f32 v221, v232, v233
	s_add_u32 s68, s68, 0x800
	s_addc_u32 s69, s69, 0
	global_store_dwordx4 v82, v[218:221], s[68:69]
	s_cmpk_lg_u32 s40, 0x7f0
	s_cbranch_scc1 .Lpl_w7_nopp9
	v_lshlrev_b32_e32 v222, 16, v176
	v_and_b32_e32 v223, 0xffff0000, v176
	v_lshlrev_b32_e32 v224, 16, v177
	v_and_b32_e32 v225, 0xffff0000, v177
	v_lshlrev_b32_e32 v226, 16, v178
	v_and_b32_e32 v227, 0xffff0000, v178
	v_lshlrev_b32_e32 v228, 16, v179
	v_and_b32_e32 v229, 0xffff0000, v179
	s_add_u32 s70, s70, 0x1000
	s_addc_u32 s71, s71, 0
	global_store_dwordx4 v185, v[222:225], s[70:71]
	global_store_dwordx4 v185, v[226:229], s[70:71] offset:16
.Lpl_w7_nopp9:
	v_cndmask_b32_e64 v129, v134, v36, s[72:73]
	v_lshlrev_b32_e32 v158, 16, v129
	v_and_b32_e32 v159, 0xffff0000, v129
	v_pk_add_f32 v[206:207], v[206:207], v[158:159] neg_lo:[0,1] neg_hi:[0,1]
	v_cndmask_b32_e64 v129, v135, v37, s[72:73]
	v_lshlrev_b32_e32 v158, 16, v129
	v_and_b32_e32 v159, 0xffff0000, v129
	v_pk_add_f32 v[208:209], v[208:209], v[158:159] neg_lo:[0,1] neg_hi:[0,1]
	v_cndmask_b32_e64 v129, v136, v38, s[72:73]
	v_lshlrev_b32_e32 v158, 16, v129
	v_and_b32_e32 v159, 0xffff0000, v129
	v_pk_add_f32 v[210:211], v[210:211], v[158:159] neg_lo:[0,1] neg_hi:[0,1]
	v_cndmask_b32_e64 v129, v137, v39, s[72:73]
	v_lshlrev_b32_e32 v158, 16, v129
	v_and_b32_e32 v159, 0xffff0000, v129
	v_pk_add_f32 v[212:213], v[212:213], v[158:159] neg_lo:[0,1] neg_hi:[0,1]
	s_waitcnt vmcnt(15)
	v_mov_b32_e32 v175, 0x3dba2e8c
	v_cmp_lt_u32_e32 vcc, 11, v65
	s_and_b64 vcc, vcc, s[78:79]
	s_nop 1
	v_cndmask_b32_e32 v234, v72, v175, vcc
	v_lshlrev_b32_e32 v230, 16, v180
	v_and_b32_e32 v231, 0xffff0000, v180
	v_pk_add_f32 v[206:207], v[206:207], v[230:231]
	v_pk_fma_f32 v[232:233], v[234:235], v[206:207], v[230:231] op_sel_hi:[0,1,1] neg_lo:[0,0,1] neg_hi:[0,0,1]
	v_cvt_pk_bf16_f32 v214, v232, v233
	v_lshlrev_b32_e32 v230, 16, v181
	v_and_b32_e32 v231, 0xffff0000, v181
	v_pk_add_f32 v[208:209], v[208:209], v[230:231]
	v_pk_fma_f32 v[232:233], v[234:235], v[208:209], v[230:231] op_sel_hi:[0,1,1] neg_lo:[0,0,1] neg_hi:[0,0,1]
	v_cvt_pk_bf16_f32 v215, v232, v233
	v_lshlrev_b32_e32 v230, 16, v182
	v_and_b32_e32 v231, 0xffff0000, v182
	v_pk_add_f32 v[210:211], v[210:211], v[230:231]
	v_pk_fma_f32 v[232:233], v[234:235], v[210:211], v[230:231] op_sel_hi:[0,1,1] neg_lo:[0,0,1] neg_hi:[0,0,1]
	v_cvt_pk_bf16_f32 v216, v232, v233
	v_lshlrev_b32_e32 v230, 16, v183
	v_and_b32_e32 v231, 0xffff0000, v183
	v_pk_add_f32 v[212:213], v[212:213], v[230:231]
	v_pk_fma_f32 v[232:233], v[234:235], v[212:213], v[230:231] op_sel_hi:[0,1,1] neg_lo:[0,0,1] neg_hi:[0,0,1]
	v_cvt_pk_bf16_f32 v217, v232, v233
	s_add_u32 s68, s68, 0x800
	s_addc_u32 s69, s69, 0
	global_store_dwordx4 v82, v[214:217], s[68:69]
	s_cmpk_lg_u32 s40, 0x7f0
	s_cbranch_scc1 .Lpl_w7_nopp10
	v_lshlrev_b32_e32 v222, 16, v180
	v_and_b32_e32 v223, 0xffff0000, v180
	v_lshlrev_b32_e32 v224, 16, v181
	v_and_b32_e32 v225, 0xffff0000, v181
	v_lshlrev_b32_e32 v226, 16, v182
	v_and_b32_e32 v227, 0xffff0000, v182
	v_lshlrev_b32_e32 v228, 16, v183
	v_and_b32_e32 v229, 0xffff0000, v183
	s_add_u32 s70, s70, 0x1000
	s_addc_u32 s71, s71, 0
	global_store_dwordx4 v185, v[222:225], s[70:71]
	global_store_dwordx4 v185, v[226:229], s[70:71] offset:16
; __device__ __forceinline__ u32x4 pack8(const float* f) { u32x4 w; w.x = pk2(f[0], f[1]); w.y = pk2(f[2], f[3]); w.z = pk2(f[4], f[5]); w.w = pk2(f[6], f[7]); return w; }
; template <int NTOK, bool SMP>
; __device__ __forceinline__ void mixer_item(const Params& p, int it) {
;     ...
;         for (int t = 0; t < NTOK; ++t) {
;             const int tt = t0 + t; float x[8], y[8], f[8];
;             xpool(tt, x);
;             const float cnt = SMP ? (float)w : (float)min(w, tt + 1); const float ic = 1.0f / cnt;
; #pragma unroll
;             for (int i = 0; i < 8; ++i) { s[i] += x[i]; y[i] = s[i] * ic - x[i]; }
;             *(u32x4*)(yp + (size_t)(seqrow0 + tt) * 1024 + pc) = pack8(y);
;             xpool(tt - w + 1, f);
; #pragma unroll
;             for (int i = 0; i < 8; ++i) s[i] -= f[i];
;             if (SMP) { float* o = p.out + O_PS + ((size_t)sb * 15 + 11 + t) * 1024 + pc; *(f32x4*)o = (f32x4){x[0], x[1], x[2], x[3]}; *(f32x4*)(o + 4) = (f32x4){x[4], x[5], x[6], x[7]}; }
;             else if (tt >= 2033) { float* o = p.out + O_PP + ((size_t)b * 15 + (tt - 2033)) * 1024 + pc; *(f32x4*)o = (f32x4){x[0], x[1], x[2], x[3]}; *(f32x4*)(o + 4) = (f32x4){x[4], x[5], x[6], x[7]}; }
.Lpl_w7_nopp10:
	v_cndmask_b32_e64 v129, v138, v40, s[72:73]
	v_lshlrev_b32_e32 v158, 16, v129
	v_and_b32_e32 v159, 0xffff0000, v129
	v_pk_add_f32 v[206:207], v[206:207], v[158:159] neg_lo:[0,1] neg_hi:[0,1]
	v_cndmask_b32_e64 v129, v139, v41, s[72:73]
	v_lshlrev_b32_e32 v158, 16, v129
	v_and_b32_e32 v159, 0xffff0000, v129
	v_pk_add_f32 v[208:209], v[208:209], v[158:159] neg_lo:[0,1] neg_hi:[0,1]
	v_cndmask_b32_e64 v129, v140, v42, s[72:73]
	v_lshlrev_b32_e32 v158, 16, v129
	v_and_b32_e32 v159, 0xffff0000, v129
	v_pk_add_f32 v[210:211], v[210:211], v[158:159] neg_lo:[0,1] neg_hi:[0,1]
	v_cndmask_b32_e64 v129, v141, v43, s[72:73]
	v_lshlrev_b32_e32 v158, 16, v129
	v_and_b32_e32 v159, 0xffff0000, v129
	v_pk_add_f32 v[212:213], v[212:213], v[158:159] neg_lo:[0,1] neg_hi:[0,1]
	s_waitcnt vmcnt(15)
	v_mov_b32_e32 v175, 0x3daaaaab
	v_cmp_lt_u32_e32 vcc, 12, v65
	s_and_b64 vcc, vcc, s[78:79]
	s_nop 1
	v_cndmask_b32_e32 v234, v72, v175, vcc
	v_lshlrev_b32_e32 v230, 16, v186
	v_and_b32_e32 v231, 0xffff0000, v186
	v_pk_add_f32 v[206:207], v[206:207], v[230:231]
	v_pk_fma_f32 v[232:233], v[234:235], v[206:207], v[230:231] op_sel_hi:[0,1,1] neg_lo:[0,0,1] neg_hi:[0,0,1]
	v_cvt_pk_bf16_f32 v218, v232, v233
	v_lshlrev_b32_e32 v230, 16, v187
	v_and_b32_e32 v231, 0xffff0000, v187
	v_pk_add_f32 v[208:209], v[208:209], v[230:231]
	v_pk_fma_f32 v[232:233], v[234:235], v[208:209], v[230:231] op_sel_hi:[0,1,1] neg_lo:[0,0,1] neg_hi:[0,0,1]
	v_cvt_pk_bf16_f32 v219, v232, v233
	v_lshlrev_b32_e32 v230, 16, v188
	v_and_b32_e32 v231, 0xffff0000, v188
	v_pk_add_f32 v[210:211], v[210:211], v[230:231]
	v_pk_fma_f32 v[232:233], v[234:235], v[210:211], v[230:231] op_sel_hi:[0,1,1] neg_lo:[0,0,1] neg_hi:[0,0,1]
	v_cvt_pk_bf16_f32 v220, v232, v233
	v_lshlrev_b32_e32 v230, 16, v189
	v_and_b32_e32 v231, 0xffff0000, v189
	v_pk_add_f32 v[212:213], v[212:213], v[230:231]
	v_pk_fma_f32 v[232:233], v[234:235], v[212:213], v[230:231] op_sel_hi:[0,1,1] neg_lo:[0,0,1] neg_hi:[0,0,1]
	v_cvt_pk_bf16_f32 v221, v232, v233
	s_add_u32 s68, s68, 0x800
	s_addc_u32 s69, s69, 0
	global_store_dwordx4 v82, v[218:221], s[68:69]
	s_cmpk_lg_u32 s40, 0x7f0
	s_cbranch_scc1 .Lpl_w7_nopp11
	v_lshlrev_b32_e32 v222, 16, v186
	v_and_b32_e32 v223, 0xffff0000, v186
	v_lshlrev_b32_e32 v224, 16, v187
	v_and_b32_e32 v225, 0xffff0000, v187
	v_lshlrev_b32_e32 v226, 16, v188
	v_and_b32_e32 v227, 0xffff0000, v188
	v_lshlrev_b32_e32 v228, 16, v189
	v_and_b32_e32 v229, 0xffff0000, v189
	s_add_u32 s70, s70, 0x1000
	s_addc_u32 s71, s71, 0
	global_store_dwordx4 v185, v[222:225], s[70:71]
	global_store_dwordx4 v185, v[226:229], s[70:71] offset:16
.Lpl_w7_nopp11:
	v_cndmask_b32_e64 v129, v142, v44, s[72:73]
	v_lshlrev_b32_e32 v158, 16, v129
	v_and_b32_e32 v159, 0xffff0000, v129
	v_pk_add_f32 v[206:207], v[206:207], v[158:159] neg_lo:[0,1] neg_hi:[0,1]
	v_cndmask_b32_e64 v129, v143, v45, s[72:73]
	v_lshlrev_b32_e32 v158, 16, v129
	v_and_b32_e32 v159, 0xffff0000, v129
	v_pk_add_f32 v[208:209], v[208:209], v[158:159] neg_lo:[0,1] neg_hi:[0,1]
	v_cndmask_b32_e64 v129, v144, v46, s[72:73]
	v_lshlrev_b32_e32 v158, 16, v129
	v_and_b32_e32 v159, 0xffff0000, v129
	v_pk_add_f32 v[210:211], v[210:211], v[158:159] neg_lo:[0,1] neg_hi:[0,1]
	v_cndmask_b32_e64 v129, v145, v47, s[72:73]
	v_lshlrev_b32_e32 v158, 16, v129
	v_and_b32_e32 v159, 0xffff0000, v129
	v_pk_add_f32 v[212:213], v[212:213], v[158:159] neg_lo:[0,1] neg_hi:[0,1]
	s_waitcnt vmcnt(15)
	v_mov_b32_e32 v175, 0x3d9d89d9
	v_cmp_lt_u32_e32 vcc, 13, v65
	s_and_b64 vcc, vcc, s[78:79]
	s_nop 1
	v_cndmask_b32_e32 v234, v72, v175, vcc
	v_lshlrev_b32_e32 v230, 16, v190
	v_and_b32_e32 v231, 0xffff0000, v190
	v_pk_add_f32 v[206:207], v[206:207], v[230:231]
	v_pk_fma_f32 v[232:233], v[234:235], v[206:207], v[230:231] op_sel_hi:[0,1,1] neg_lo:[0,0,1] neg_hi:[0,0,1]
	v_cvt_pk_bf16_f32 v214, v232, v233
	v_lshlrev_b32_e32 v230, 16, v191
	v_and_b32_e32 v231, 0xffff0000, v191
	v_pk_add_f32 v[208:209], v[208:209], v[230:231]
	v_pk_fma_f32 v[232:233], v[234:235], v[208:209], v[230:231] op_sel_hi:[0,1,1] neg_lo:[0,0,1] neg_hi:[0,0,1]
	v_cvt_pk_bf16_f32 v215, v232, v233
	v_lshlrev_b32_e32 v230, 16, v192
	v_and_b32_e32 v231, 0xffff0000, v192
	v_pk_add_f32 v[210:211], v[210:211], v[230:231]
	v_pk_fma_f32 v[232:233], v[234:235], v[210:211], v[230:231] op_sel_hi:[0,1,1] neg_lo:[0,0,1] neg_hi:[0,0,1]
	v_cvt_pk_bf16_f32 v216, v232, v233
	v_lshlrev_b32_e32 v230, 16, v193
	v_and_b32_e32 v231, 0xffff0000, v193
	v_pk_add_f32 v[212:213], v[212:213], v[230:231]
	v_pk_fma_f32 v[232:233], v[234:235], v[212:213], v[230:231] op_sel_hi:[0,1,1] neg_lo:[0,0,1] neg_hi:[0,0,1]
	v_cvt_pk_bf16_f32 v217, v232, v233
	s_add_u32 s68, s68, 0x800
	s_addc_u32 s69, s69, 0
	global_store_dwordx4 v82, v[214:217], s[68:69]
	s_cmpk_lg_u32 s40, 0x7f0
	s_cbranch_scc1 .Lpl_w7_nopp12
	v_lshlrev_b32_e32 v222, 16, v190
	v_and_b32_e32 v223, 0xffff0000, v190
	v_lshlrev_b32_e32 v224, 16, v191
	v_and_b32_e32 v225, 0xffff0000, v191
	v_lshlrev_b32_e32 v226, 16, v192
	v_and_b32_e32 v227, 0xffff0000, v192
	v_lshlrev_b32_e32 v228, 16, v193
	v_and_b32_e32 v229, 0xffff0000, v193
	s_add_u32 s70, s70, 0x1000
	s_addc_u32 s71, s71, 0
	global_store_dwordx4 v185, v[222:225], s[70:71]
	global_store_dwordx4 v185, v[226:229], s[70:71] offset:16
; __device__ __forceinline__ u32x4 pack8(const float* f) { u32x4 w; w.x = pk2(f[0], f[1]); w.y = pk2(f[2], f[3]); w.z = pk2(f[4], f[5]); w.w = pk2(f[6], f[7]); return w; }
; template <int NTOK, bool SMP>
; __device__ __forceinline__ void mixer_item(const Params& p, int it) {
;     ...
;         for (int t = 0; t < NTOK; ++t) {
;             const int tt = t0 + t; float x[8], y[8], f[8];
;             xpool(tt, x);
;             const float cnt = SMP ? (float)w : (float)min(w, tt + 1); const float ic = 1.0f / cnt;
; #pragma unroll
;             for (int i = 0; i < 8; ++i) { s[i] += x[i]; y[i] = s[i] * ic - x[i]; }
;             *(u32x4*)(yp + (size_t)(seqrow0 + tt) * 1024 + pc) = pack8(y);
;             xpool(tt - w + 1, f);
; #pragma unroll
;             for (int i = 0; i < 8; ++i) s[i] -= f[i];
;             if (SMP) { float* o = p.out + O_PS + ((size_t)sb * 15 + 11 + t) * 1024 + pc; *(f32x4*)o = (f32x4){x[0], x[1], x[2], x[3]}; *(f32x4*)(o + 4) = (f32x4){x[4], x[5], x[6], x[7]}; }
;             else if (tt >= 2033) { float* o = p.out + O_PP + ((size_t)b * 15 + (tt - 2033)) * 1024 + pc; *(f32x4*)o = (f32x4){x[0], x[1], x[2], x[3]}; *(f32x4*)(o + 4) = (f32x4){x[4], x[5], x[6], x[7]}; }
.Lpl_w7_nopp12:
	v_cndmask_b32_e64 v129, v146, v48, s[72:73]
	v_lshlrev_b32_e32 v158, 16, v129
	v_and_b32_e32 v159, 0xffff0000, v129
	v_pk_add_f32 v[206:207], v[206:207], v[158:159] neg_lo:[0,1] neg_hi:[0,1]
	v_cndmask_b32_e64 v129, v147, v49, s[72:73]
	v_lshlrev_b32_e32 v158, 16, v129
	v_and_b32_e32 v159, 0xffff0000, v129
	v_pk_add_f32 v[208:209], v[208:209], v[158:159] neg_lo:[0,1] neg_hi:[0,1]
	v_cndmask_b32_e64 v129, v148, v50, s[72:73]
	v_lshlrev_b32_e32 v158, 16, v129
	v_and_b32_e32 v159, 0xffff0000, v129
	v_pk_add_f32 v[210:211], v[210:211], v[158:159] neg_lo:[0,1] neg_hi:[0,1]
	v_cndmask_b32_e64 v129, v149, v51, s[72:73]
	v_lshlrev_b32_e32 v158, 16, v129
	v_and_b32_e32 v159, 0xffff0000, v129
	v_pk_add_f32 v[212:213], v[212:213], v[158:159] neg_lo:[0,1] neg_hi:[0,1]
	s_waitcnt vmcnt(15)
	v_mov_b32_e32 v175, 0x3d924925
	v_cmp_lt_u32_e32 vcc, 14, v65
	s_and_b64 vcc, vcc, s[78:79]
	s_nop 1
	v_cndmask_b32_e32 v234, v72, v175, vcc
	v_lshlrev_b32_e32 v230, 16, v194
	v_and_b32_e32 v231, 0xffff0000, v194
	v_pk_add_f32 v[206:207], v[206:207], v[230:231]
	v_pk_fma_f32 v[232:233], v[234:235], v[206:207], v[230:231] op_sel_hi:[0,1,1] neg_lo:[0,0,1] neg_hi:[0,0,1]
	v_cvt_pk_bf16_f32 v218, v232, v233
	v_lshlrev_b32_e32 v230, 16, v195
	v_and_b32_e32 v231, 0xffff0000, v195
	v_pk_add_f32 v[208:209], v[208:209], v[230:231]
	v_pk_fma_f32 v[232:233], v[234:235], v[208:209], v[230:231] op_sel_hi:[0,1,1] neg_lo:[0,0,1] neg_hi:[0,0,1]
	v_cvt_pk_bf16_f32 v219, v232, v233
	v_lshlrev_b32_e32 v230, 16, v196
	v_and_b32_e32 v231, 0xffff0000, v196
	v_pk_add_f32 v[210:211], v[210:211], v[230:231]
	v_pk_fma_f32 v[232:233], v[234:235], v[210:211], v[230:231] op_sel_hi:[0,1,1] neg_lo:[0,0,1] neg_hi:[0,0,1]
	v_cvt_pk_bf16_f32 v220, v232, v233
	v_lshlrev_b32_e32 v230, 16, v197
	v_and_b32_e32 v231, 0xffff0000, v197
	v_pk_add_f32 v[212:213], v[212:213], v[230:231]
	v_pk_fma_f32 v[232:233], v[234:235], v[212:213], v[230:231] op_sel_hi:[0,1,1] neg_lo:[0,0,1] neg_hi:[0,0,1]
	v_cvt_pk_bf16_f32 v221, v232, v233
	s_add_u32 s68, s68, 0x800
	s_addc_u32 s69, s69, 0
	global_store_dwordx4 v82, v[218:221], s[68:69]
	s_cmpk_lg_u32 s40, 0x7f0
	s_cbranch_scc1 .Lpl_w7_nopp13
	v_lshlrev_b32_e32 v222, 16, v194
	v_and_b32_e32 v223, 0xffff0000, v194
	v_lshlrev_b32_e32 v224, 16, v195
	v_and_b32_e32 v225, 0xffff0000, v195
	v_lshlrev_b32_e32 v226, 16, v196
	v_and_b32_e32 v227, 0xffff0000, v196
	v_lshlrev_b32_e32 v228, 16, v197
	v_and_b32_e32 v229, 0xffff0000, v197
	s_add_u32 s70, s70, 0x1000
	s_addc_u32 s71, s71, 0
	global_store_dwordx4 v185, v[222:225], s[70:71]
	global_store_dwordx4 v185, v[226:229], s[70:71] offset:16
; __device__ __forceinline__ u32x4 pack8(const float* f) { u32x4 w; w.x = pk2(f[0], f[1]); w.y = pk2(f[2], f[3]); w.z = pk2(f[4], f[5]); w.w = pk2(f[6], f[7]); return w; }
; template <int NTOK, bool SMP>
; __device__ __forceinline__ void mixer_item(const Params& p, int it) {
;     ...
;         for (int t = 0; t < NTOK; ++t) {
;             const int tt = t0 + t; float x[8], y[8], f[8];
;             xpool(tt, x);
;             const float cnt = SMP ? (float)w : (float)min(w, tt + 1); const float ic = 1.0f / cnt;
; #pragma unroll
;             for (int i = 0; i < 8; ++i) { s[i] += x[i]; y[i] = s[i] * ic - x[i]; }
;             *(u32x4*)(yp + (size_t)(seqrow0 + tt) * 1024 + pc) = pack8(y);
;             xpool(tt - w + 1, f);
; #pragma unroll
;             for (int i = 0; i < 8; ++i) s[i] -= f[i];
;             if (SMP) { float* o = p.out + O_PS + ((size_t)sb * 15 + 11 + t) * 1024 + pc; *(f32x4*)o = (f32x4){x[0], x[1], x[2], x[3]}; *(f32x4*)(o + 4) = (f32x4){x[4], x[5], x[6], x[7]}; }
;             else if (tt >= 2033) { float* o = p.out + O_PP + ((size_t)b * 15 + (tt - 2033)) * 1024 + pc; *(f32x4*)o = (f32x4){x[0], x[1], x[2], x[3]}; *(f32x4*)(o + 4) = (f32x4){x[4], x[5], x[6], x[7]}; }
.Lpl_w7_nopp13:
	v_cndmask_b32_e64 v129, v150, v52, s[72:73]
	v_lshlrev_b32_e32 v158, 16, v129
	v_and_b32_e32 v159, 0xffff0000, v129
	v_pk_add_f32 v[206:207], v[206:207], v[158:159] neg_lo:[0,1] neg_hi:[0,1]
	v_cndmask_b32_e64 v129, v151, v53, s[72:73]
	v_lshlrev_b32_e32 v158, 16, v129
	v_and_b32_e32 v159, 0xffff0000, v129
	v_pk_add_f32 v[208:209], v[208:209], v[158:159] neg_lo:[0,1] neg_hi:[0,1]
	v_cndmask_b32_e64 v129, v152, v54, s[72:73]
	v_lshlrev_b32_e32 v158, 16, v129
	v_and_b32_e32 v159, 0xffff0000, v129
	v_pk_add_f32 v[210:211], v[210:211], v[158:159] neg_lo:[0,1] neg_hi:[0,1]
	v_cndmask_b32_e64 v129, v153, v55, s[72:73]
	v_lshlrev_b32_e32 v158, 16, v129
	v_and_b32_e32 v159, 0xffff0000, v129
	v_pk_add_f32 v[212:213], v[212:213], v[158:159] neg_lo:[0,1] neg_hi:[0,1]
	s_waitcnt vmcnt(15)
	v_mov_b32_e32 v175, 0x3d888889
	v_cmp_lt_u32_e32 vcc, 15, v65
	s_and_b64 vcc, vcc, s[78:79]
	s_nop 1
	v_cndmask_b32_e32 v234, v72, v175, vcc
	v_lshlrev_b32_e32 v230, 16, v198
	v_and_b32_e32 v231, 0xffff0000, v198
	v_pk_add_f32 v[206:207], v[206:207], v[230:231]
	v_pk_fma_f32 v[232:233], v[234:235], v[206:207], v[230:231] op_sel_hi:[0,1,1] neg_lo:[0,0,1] neg_hi:[0,0,1]
	v_cvt_pk_bf16_f32 v214, v232, v233
	v_lshlrev_b32_e32 v230, 16, v199
	v_and_b32_e32 v231, 0xffff0000, v199
	v_pk_add_f32 v[208:209], v[208:209], v[230:231]
	v_pk_fma_f32 v[232:233], v[234:235], v[208:209], v[230:231] op_sel_hi:[0,1,1] neg_lo:[0,0,1] neg_hi:[0,0,1]
	v_cvt_pk_bf16_f32 v215, v232, v233
	v_lshlrev_b32_e32 v230, 16, v200
	v_and_b32_e32 v231, 0xffff0000, v200
	v_pk_add_f32 v[210:211], v[210:211], v[230:231]
	v_pk_fma_f32 v[232:233], v[234:235], v[210:211], v[230:231] op_sel_hi:[0,1,1] neg_lo:[0,0,1] neg_hi:[0,0,1]
	v_cvt_pk_bf16_f32 v216, v232, v233
	v_lshlrev_b32_e32 v230, 16, v201
	v_and_b32_e32 v231, 0xffff0000, v201
	v_pk_add_f32 v[212:213], v[212:213], v[230:231]
	v_pk_fma_f32 v[232:233], v[234:235], v[212:213], v[230:231] op_sel_hi:[0,1,1] neg_lo:[0,0,1] neg_hi:[0,0,1]
	v_cvt_pk_bf16_f32 v217, v232, v233
	s_add_u32 s68, s68, 0x800
	s_addc_u32 s69, s69, 0
	global_store_dwordx4 v82, v[214:217], s[68:69]
	s_cmpk_lg_u32 s40, 0x7f0
	s_cbranch_scc1 .Lpl_w7_nopp14
	v_lshlrev_b32_e32 v222, 16, v198
	v_and_b32_e32 v223, 0xffff0000, v198
	v_lshlrev_b32_e32 v224, 16, v199
	v_and_b32_e32 v225, 0xffff0000, v199
	v_lshlrev_b32_e32 v226, 16, v200
	v_and_b32_e32 v227, 0xffff0000, v200
	v_lshlrev_b32_e32 v228, 16, v201
	v_and_b32_e32 v229, 0xffff0000, v201
	s_add_u32 s70, s70, 0x1000
	s_addc_u32 s71, s71, 0
	global_store_dwordx4 v185, v[222:225], s[70:71]
	global_store_dwordx4 v185, v[226:229], s[70:71] offset:16
.Lpl_w7_nopp14:
	v_cndmask_b32_e64 v129, v154, v56, s[72:73]
	v_lshlrev_b32_e32 v158, 16, v129
	v_and_b32_e32 v159, 0xffff0000, v129
	v_pk_add_f32 v[206:207], v[206:207], v[158:159] neg_lo:[0,1] neg_hi:[0,1]
	v_cndmask_b32_e64 v129, v155, v57, s[72:73]
	v_lshlrev_b32_e32 v158, 16, v129
	v_and_b32_e32 v159, 0xffff0000, v129
	v_pk_add_f32 v[208:209], v[208:209], v[158:159] neg_lo:[0,1] neg_hi:[0,1]
	v_cndmask_b32_e64 v129, v156, v58, s[72:73]
	v_lshlrev_b32_e32 v158, 16, v129
	v_and_b32_e32 v159, 0xffff0000, v129
	v_pk_add_f32 v[210:211], v[210:211], v[158:159] neg_lo:[0,1] neg_hi:[0,1]
	v_cndmask_b32_e64 v129, v157, v59, s[72:73]
	v_lshlrev_b32_e32 v158, 16, v129
	v_and_b32_e32 v159, 0xffff0000, v129
	v_pk_add_f32 v[212:213], v[212:213], v[158:159] neg_lo:[0,1] neg_hi:[0,1]
	s_waitcnt vmcnt(15)
	v_lshlrev_b32_e32 v230, 16, v202
	v_and_b32_e32 v231, 0xffff0000, v202
	v_pk_add_f32 v[206:207], v[206:207], v[230:231]
	v_pk_fma_f32 v[232:233], v[72:73], v[206:207], v[230:231] op_sel_hi:[0,1,1] neg_lo:[0,0,1] neg_hi:[0,0,1]
	v_cvt_pk_bf16_f32 v218, v232, v233
	v_lshlrev_b32_e32 v230, 16, v203
	v_and_b32_e32 v231, 0xffff0000, v203
	v_pk_add_f32 v[208:209], v[208:209], v[230:231]
	v_pk_fma_f32 v[232:233], v[72:73], v[208:209], v[230:231] op_sel_hi:[0,1,1] neg_lo:[0,0,1] neg_hi:[0,0,1]
	v_cvt_pk_bf16_f32 v219, v232, v233
	v_lshlrev_b32_e32 v230, 16, v204
	v_and_b32_e32 v231, 0xffff0000, v204
	v_pk_add_f32 v[210:211], v[210:211], v[230:231]
	v_pk_fma_f32 v[232:233], v[72:73], v[210:211], v[230:231] op_sel_hi:[0,1,1] neg_lo:[0,0,1] neg_hi:[0,0,1]
	v_cvt_pk_bf16_f32 v220, v232, v233
	v_lshlrev_b32_e32 v230, 16, v205
	v_and_b32_e32 v231, 0xffff0000, v205
	v_pk_add_f32 v[212:213], v[212:213], v[230:231]
	v_pk_fma_f32 v[232:233], v[72:73], v[212:213], v[230:231] op_sel_hi:[0,1,1] neg_lo:[0,0,1] neg_hi:[0,0,1]
	v_cvt_pk_bf16_f32 v221, v232, v233
	s_add_u32 s68, s68, 0x800
	s_addc_u32 s69, s69, 0
	global_store_dwordx4 v82, v[218:221], s[68:69]
	s_cmpk_lg_u32 s40, 0x7f0
	s_cbranch_scc1 .Lpl_w7_nopp15
	v_lshlrev_b32_e32 v222, 16, v202
	v_and_b32_e32 v223, 0xffff0000, v202
	v_lshlrev_b32_e32 v224, 16, v203
	v_and_b32_e32 v225, 0xffff0000, v203
	v_lshlrev_b32_e32 v226, 16, v204
	v_and_b32_e32 v227, 0xffff0000, v204
	v_lshlrev_b32_e32 v228, 16, v205
	v_and_b32_e32 v229, 0xffff0000, v205
	s_add_u32 s70, s70, 0x1000
	s_addc_u32 s71, s71, 0
	global_store_dwordx4 v185, v[222:225], s[70:71]
	global_store_dwordx4 v185, v[226:229], s[70:71] offset:16

; template <int NTOK, bool SMP>
; __device__ __forceinline__ void mixer_item(const Params& p, int it) {
;     ...
;         } else if (t0 == 0) {
; #pragma unroll
;             for (int i = 0; i < 8; ++i) { xm3[i] = 0.f; xm2[i] = 0.f; xm1[i] = 0.f; }
;         } else {
;             unpack8(*(const u32x4*)(proj + (size_t)(rowbase - 3) * NPROJ + c0), xm3); unpack8(*(const u32x4*)(proj + (size_t)(rowbase - 2) * NPROJ + c0), xm2); unpack8(*(const u32x4*)(proj + (size_t)(rowbase - 1) * NPROJ + c0), xm1);
;         }
;         constexpr int CH = NTOK < 8 ? NTOK : 8;
; #pragma unroll
;         for (int tc = 0; tc < NTOK; tc += CH) {
;         u32x4 xr[CH];
; #pragma unroll
;         for (int t = 0; t < CH; ++t) xr[t] = *(const u32x4*)(proj + (size_t)(rowbase + tc + t) * NPROJ + c0);
.LBB0_547:
	s_and_b64 vcc, exec, s[22:23]
	s_cbranch_vccz .LBB0_540
	s_branch .LBB0_816
.LBB0_637:
	s_andn2_saveexec_b64 s[22:23], s[62:63]
	s_cbranch_execz .LBB0_807
	global_load_dwordx4 v[0:3], v[88:89], off offset:16
	global_load_dwordx4 v[16:19], v[88:89], off
	global_load_dwordx4 v[4:7], v[90:91], off offset:16
	global_load_dwordx4 v[28:31], v[90:91], off
	global_load_dwordx4 v[8:11], v[92:93], off offset:16
	global_load_dwordx4 v[20:23], v[92:93], off
	global_load_dwordx4 v[12:15], v[94:95], off offset:16
	global_load_dwordx4 v[24:27], v[94:95], off
	s_cmp_eq_u32 s40, 0
	s_cbranch_scc1 .LBB0_640
	s_add_i32 s61, s60, -3
	v_mad_i64_i32 v[32:33], s[62:63], s61, v168, v[80:81]
	s_add_i32 s61, s60, -2
	v_mad_i64_i32 v[36:37], s[62:63], s61, v168, v[80:81]
	s_add_i32 s61, s60, -1
	v_mad_i64_i32 v[40:41], s[62:63], s61, v168, v[80:81]
	global_load_dwordx4 v[32:35], v[32:33], off
	s_nop 0
	global_load_dwordx4 v[36:39], v[36:37], off
	s_waitcnt vmcnt(1)
	v_lshlrev_b32_e32 v144, 16, v32
	global_load_dwordx4 v[40:43], v[40:41], off
	v_and_b32_e32 v145, 0xffff0000, v32
	v_lshlrev_b32_e32 v142, 16, v33
	v_and_b32_e32 v143, 0xffff0000, v33
	v_lshlrev_b32_e32 v130, 16, v34
	v_and_b32_e32 v131, 0xffff0000, v34
	v_lshlrev_b32_e32 v140, 16, v35
	v_and_b32_e32 v141, 0xffff0000, v35
	s_waitcnt vmcnt(1)
	v_lshlrev_b32_e32 v152, 16, v36
	v_and_b32_e32 v153, 0xffff0000, v36
	v_lshlrev_b32_e32 v148, 16, v37
	v_and_b32_e32 v149, 0xffff0000, v37
	v_lshlrev_b32_e32 v132, 16, v38
	v_and_b32_e32 v133, 0xffff0000, v38
	v_lshlrev_b32_e32 v164, 16, v39
	v_and_b32_e32 v146, 0xffff0000, v39
	s_waitcnt vmcnt(0)
	v_lshlrev_b32_e32 v138, 16, v40
	v_and_b32_e32 v139, 0xffff0000, v40
	v_lshlrev_b32_e32 v136, 16, v41
	v_and_b32_e32 v137, 0xffff0000, v41
	v_lshlrev_b32_e32 v134, 16, v42
	v_and_b32_e32 v135, 0xffff0000, v42
	v_lshlrev_b32_e32 v129, 16, v43
	v_and_b32_e32 v147, 0xffff0000, v43
	s_branch .LBB0_641
